# plus scan items: gate-weight quads loaded at the start of the item (next to the conv bias loads) instead of right before their LDS writes
# speedup vs baseline: 1.0003x; 1.0003x over previous
.LBB0_892:
	s_or_b64 exec, exec, s[30:31]
	s_lshl_b32 s44, s47, 6
	s_lshl_b32 s25, s24, 3
	s_and_b32 s25, s25, 0x7fffff00
	s_and_b32 s34, s44, 0x7ffff000
	s_and_b64 s[30:31], s[28:29], exec
	s_cselect_b32 s30, 0x100, s38
	s_cselect_b32 s37, s25, s34
	s_add_i32 s36, s37, s30
	s_barrier
	s_load_dwordx2 s[34:35], s[22:23], 0xa0
	s_add_u32 s30, s26, 0xaa08000
	v_lshlrev_b32_e32 v0, 4, v72
	s_addc_u32 s31, s27, 0
	v_and_b32_e32 v1, 48, v0
	s_lshl_b32 s25, s46, 6
	v_or_b32_e32 v2, s25, v1
	v_lshlrev_b32_e32 v20, 2, v2
	s_waitcnt lgkmcnt(0)
	global_load_dwordx4 v[8:11], v20, s[34:35] offset:48
	global_load_dwordx4 v[4:7], v20, s[34:35] offset:32
	global_load_dwordx4 v[16:19], v20, s[34:35] offset:16
	global_load_dwordx4 v[12:15], v20, s[34:35]
	s_lshl_b32 s35, s46, 13
	s_add_u32 s34, s26, s35
	s_addc_u32 s35, s27, 0
	s_add_u32 s34, s34, 0x2d00000
	s_addc_u32 s35, s35, 0
	v_bfe_u32 v174, v200, 3, 5
	v_and_b32_e32 v175, 7, v200
	v_lshlrev_b32_e32 v174, 7, v174
	v_lshl_or_b32 v174, v175, 4, v174
	global_load_dwordx4 v[184:187], v174, s[34:35]
	v_add_u32_e32 v175, 0x1000, v174
	global_load_dwordx4 v[188:191], v175, s[34:35]
	v_add_u32_e32 v176, 0x10000, v174
	global_load_dwordx4 v[192:195], v176, s[34:35]
	v_add_u32_e32 v175, 0x11000, v174
	global_load_dwordx4 v[196:199], v175, s[34:35]
	v_add_u32_e32 v176, 0x20000, v174
	global_load_dwordx4 v[238:241], v176, s[34:35]
	v_add_u32_e32 v175, 0x21000, v174
	global_load_dwordx4 v[242:245], v175, s[34:35]
	v_add_u32_e32 v176, 0x30000, v174
	global_load_dwordx4 v[246:249], v176, s[34:35]
	v_add_u32_e32 v175, 0x31000, v174
	global_load_dwordx4 v[250:253], v175, s[34:35]
	v_lshrrev_b32_e32 v73, 2, v72
	v_or_b32_e32 v0, s44, v73
	v_add_u32_e32 v21, -2, v0
	v_lshlrev_b32_e32 v2, 1, v2
	v_cmp_le_i32_e32 vcc, s37, v21
	v_cmp_gt_i32_e64 s[44:45], s36, v21
	v_lshl_add_u64 v[22:23], s[30:31], 0, v[2:3]
	s_load_dwordx2 s[44:45], s[22:23], 0x98
	v_mov_b32_e32 v74, 0
	v_mov_b32_e32 v75, 0
	v_mov_b32_e32 v76, 0
	v_mov_b32_e32 v77, 0
	v_mov_b32_e32 v78, 0
	v_mov_b32_e32 v79, 0
	v_mov_b32_e32 v80, 0
	v_mov_b32_e32 v81, 0
	v_mov_b32_e32 v82, 0
	v_mov_b32_e32 v83, 0
	v_mov_b32_e32 v84, 0
	v_mov_b32_e32 v85, 0
	v_mov_b32_e32 v86, 0
	v_mov_b32_e32 v87, 0
	v_mov_b32_e32 v88, 0
	v_mov_b32_e32 v89, 0
	v_mov_b32_e32 v90, 0
	v_mov_b32_e32 v91, 0
	v_mov_b32_e32 v92, 0
	v_mov_b32_e32 v93, 0
	v_mov_b32_e32 v94, 0
	v_mov_b32_e32 v95, 0
	v_mov_b32_e32 v96, 0
	v_mov_b32_e32 v97, 0
	v_mov_b32_e32 v98, 0
	v_mov_b32_e32 v99, 0
	v_mov_b32_e32 v100, 0
	v_mov_b32_e32 v101, 0
	v_mov_b32_e32 v102, 0
	v_mov_b32_e32 v103, 0
	v_mov_b32_e32 v104, 0
	v_mov_b32_e32 v105, 0
	v_add_u32_e32 v108, 0x1000, v20
	v_add_u32_e32 v109, -2, v0
	v_cmp_le_i32_e32 vcc, s37, v109
	v_cmp_gt_i32_e64 s[34:35], s36, v109
	s_and_b64 vcc, vcc, s[34:35]
	s_and_saveexec_b64 s[34:35], vcc
	s_cbranch_execz .Lcvb_0
	v_mad_u64_u32 v[106:107], vcc, v109, s97, v[22:23]
	global_load_dwordx4 v[74:77], v[106:107], off
	global_load_dwordx4 v[78:81], v[106:107], off offset:16

.LBB0_900:
	s_or_b64 exec, exec, s[34:35]
	s_lshl_b32 s34, s46, 13
	s_add_u32 s36, s26, s34
	v_lshlrev_b32_e32 v2, 4, v24
	v_lshrrev_b32_e32 v25, 3, v72
	s_addc_u32 s37, s27, 0
	v_and_b32_e32 v54, 0x70, v2
	s_add_u32 s34, s36, 0x2d00000
	v_lshlrev_b32_e32 v2, 7, v25
	s_addc_u32 s35, s37, 0
	v_or_b32_e32 v46, 0x1000, v2
	v_mov_b32_e32 v47, v3
	v_lshl_add_u64 v[20:21], s[34:35], 0, v[2:3]
	v_lshl_add_u64 v[22:23], s[34:35], 0, v[46:47]
	s_add_u32 s34, s36, 0x2d10000
	s_addc_u32 s35, s37, 0
	v_lshl_add_u64 v[30:31], s[34:35], 0, v[2:3]
	v_lshl_add_u64 v[32:33], s[34:35], 0, v[46:47]
	s_add_u32 s34, s36, 0x2d20000
	s_addc_u32 s35, s37, 0
	v_lshl_add_u64 v[38:39], s[34:35], 0, v[2:3]
	v_lshl_add_u64 v[40:41], s[34:35], 0, v[46:47]
	s_add_u32 s34, s36, 0x2d30000
	s_addc_u32 s35, s37, 0
	v_mov_b32_e32 v55, v3
	v_lshl_add_u64 v[48:49], s[34:35], 0, v[2:3]
	v_lshl_add_u64 v[46:47], s[34:35], 0, v[46:47]
	v_lshl_add_u64 v[20:21], v[20:21], 0, v[54:55]
	v_lshl_add_u64 v[26:27], v[22:23], 0, v[54:55]
	v_lshl_add_u64 v[30:31], v[30:31], 0, v[54:55]
	v_lshl_add_u64 v[34:35], v[32:33], 0, v[54:55]
	v_lshl_add_u64 v[38:39], v[38:39], 0, v[54:55]
	v_lshl_add_u64 v[42:43], v[40:41], 0, v[54:55]
	v_lshl_add_u64 v[48:49], v[48:49], 0, v[54:55]
	v_lshl_add_u64 v[50:51], v[46:47], 0, v[54:55]
	s_nop 0
	s_nop 0
	s_nop 0
	s_nop 0
	s_nop 0
	s_nop 0
	s_nop 0
	s_nop 0
	s_nop 0
	s_nop 0
	s_nop 0
	s_nop 0
	s_nop 0
	s_nop 0
	s_nop 0
	v_and_b32_e32 v2, 31, v24
	v_lshrrev_b32_e32 v114, 5, v71
	s_waitcnt vmcnt(11)
	v_cvt_pk_f16_f32 v11, v10, v11
	v_cvt_pk_f16_f32 v10, v8, v9
	s_waitcnt vmcnt(10)
	v_cvt_pk_f16_f32 v8, v4, v5
	v_mul_u32_u24_e32 v4, 0x90, v73
	v_lshlrev_b32_e32 v68, 1, v1
	v_lshlrev_b32_e32 v5, 5, v70
	s_waitcnt vmcnt(9)
	v_cvt_pk_f16_f32 v19, v18, v19
	v_cvt_pk_f16_f32 v18, v16, v17
	s_waitcnt vmcnt(8)
	v_cvt_pk_f16_f32 v17, v14, v15
	v_cvt_pk_f16_f32 v16, v12, v13
	v_cvt_pk_f16_f32 v9, v6, v7
	v_add3_u32 v4, s51, v4, v68
	v_mul_u32_u24_e32 v6, 0x90, v25
	v_and_or_b32 v116, v5, 32, v2
	v_lshlrev_b32_e32 v13, 4, v114
	v_mul_u32_u24_e32 v2, 0x90, v2
	ds_write_b128 v4, v[16:19]
	ds_write_b128 v4, v[8:11] offset:16
	v_add3_u32 v4, s51, v6, v54
	v_add3_u32 v2, s51, v2, v13
	v_lshrrev_b32_e32 v115, 7, v72
	v_mov_b32_e32 v12, s51
	s_movk_i32 s34, 0x4800
	v_mad_u32_u24 v8, v115, s34, v12
	v_mul_u32_u24_e32 v9, 0x90, v116
	s_waitcnt vmcnt(7)
	ds_write_b128 v4, v[184:187] offset:9216
	s_waitcnt vmcnt(6)
	ds_write_b128 v4, v[188:191] offset:13824
	s_waitcnt vmcnt(5)
	ds_write_b128 v4, v[192:195] offset:18432
	s_waitcnt vmcnt(4)
	ds_write_b128 v4, v[196:199] offset:23040
	s_waitcnt vmcnt(3)
	ds_write_b128 v4, v[238:241] offset:27648
	s_waitcnt vmcnt(2)
	ds_write_b128 v4, v[242:245] offset:32256
	s_waitcnt vmcnt(1)
	ds_write_b128 v4, v[246:249] offset:36864
	s_waitcnt vmcnt(0)
	ds_write_b128 v4, v[250:253] offset:41472
	s_waitcnt lgkmcnt(0)
	s_barrier
	ds_read_b128 v[4:7], v2
	v_add3_u32 v48, v8, v9, v13
	ds_read_b128 v[36:39], v48 offset:9216
	ds_read_b128 v[40:43], v2 offset:32
	ds_read_b128 v[74:77], v48 offset:9248
	ds_read_b128 v[52:55], v48 offset:18432
	ds_read_b128 v[78:81], v48 offset:18464
	s_waitcnt lgkmcnt(4)
	v_mfma_f32_32x32x16_f16 v[20:35], v[4:7], v[36:39], 0
	v_mul_u32_u24_e32 v49, 0x240, v114
	v_lshlrev_b32_e32 v50, 1, v116
	v_add3_u32 v51, s51, v50, v49
	v_add3_u32 v60, s51, v49, v50
	ds_read_b128 v[82:85], v48 offset:9280
	s_waitcnt lgkmcnt(2)
	v_mfma_f32_32x32x16_f16 v[4:19], v[4:7], v[52:55], 0
	v_mfma_f32_32x32x16_f16 v[20:35], v[40:43], v[74:77], v[20:35]
	s_waitcnt lgkmcnt(1)
	v_mfma_f32_32x32x16_f16 v[4:19], v[40:43], v[78:81], v[4:19]
	ds_read_b128 v[40:43], v2 offset:64
	ds_read_b128 v[44:47], v2 offset:96
	ds_read_b128 v[94:97], v48 offset:9312
	ds_read_b128 v[98:101], v48 offset:18496
	ds_read_b128 v[56:59], v2 offset:4608
	ds_read_b128 v[86:89], v2 offset:4640
	ds_read_b128 v[102:105], v2 offset:4672
	ds_read_b128 v[106:109], v2 offset:4704
	ds_read_b128 v[110:113], v48 offset:18528
	ds_read_u16 v90, v51
	ds_read_u16 v91, v51 offset:144
	ds_read_u16 v92, v51 offset:288
	ds_read_u16 v93, v51 offset:432
	ds_read_u16 v117, v51 offset:1152
	ds_read_u16 v118, v51 offset:1296
	ds_read_u16 v119, v51 offset:1440
	ds_read_u16 v120, v51 offset:1584
	ds_read_u16 v121, v60 offset:4608
	ds_read_u16 v122, v60 offset:4752
	ds_read_u16 v123, v60 offset:4896
	ds_read_u16 v124, v60 offset:5040
	ds_read_u16 v125, v60 offset:5760
	ds_read_u16 v126, v60 offset:5904
	ds_read_u16 v127, v60 offset:6048
	ds_read_u16 v128, v60 offset:6192
	ds_read_u16 v129, v51 offset:2304
	ds_read_u16 v130, v51 offset:2448
	ds_read_u16 v131, v51 offset:2592
	ds_read_u16 v132, v51 offset:2736
	ds_read_u16 v133, v51 offset:3456
	ds_read_u16 v134, v51 offset:3600
	ds_read_u16 v135, v51 offset:3744
	ds_read_u16 v136, v51 offset:3888
	ds_read_u16 v137, v60 offset:6912
	ds_read_u16 v138, v60 offset:7056
	ds_read_u16 v139, v60 offset:7200
	ds_read_u16 v140, v60 offset:7344
	ds_read_u16 v141, v60 offset:8064
	ds_read_u16 v142, v60 offset:8208
	ds_read_u16 v143, v60 offset:8352
	ds_read_u16 v144, v60 offset:8496
	s_waitcnt lgkmcnt(0)
	s_barrier
	s_load_dwordx4 s[44:47], s[22:23], 0xc0
	s_load_dwordx2 s[34:35], s[22:23], 0xb0
	v_lshlrev_b32_e32 v2, 9, v115
	v_or3_b32 v2, v116, v2, s25
	v_lshlrev_b32_e32 v2, 2, v2
	s_waitcnt lgkmcnt(0)
	global_load_dword v145, v2, s[46:47]
	v_mfma_f32_32x32x16_f16 v[20:35], v[40:43], v[82:85], v[20:35]
	v_cvt_f32_f16_e32 v146, v90
	v_cvt_f32_f16_e32 v147, v91
	v_cvt_f32_f16_e32 v121, v121
	v_cvt_f32_f16_e32 v122, v122
	v_cvt_f32_f16_e32 v148, v92
	v_cvt_f32_f16_e32 v149, v93
	v_cvt_f32_f16_e32 v123, v123
	v_mfma_f32_32x32x16_f16 v[4:19], v[40:43], v[98:101], v[4:19]
	v_cvt_f32_f16_e32 v124, v124
	v_cvt_f32_f16_e32 v117, v117
	v_cvt_f32_f16_e32 v118, v118
	v_cvt_f32_f16_e32 v125, v125
	v_cvt_f32_f16_e32 v126, v126
	v_cvt_f32_f16_e32 v119, v119
	v_cvt_f32_f16_e32 v92, v120
	v_mfma_f32_32x32x16_f16 v[20:35], v[44:47], v[94:97], v[20:35]
	v_cvt_f32_f16_e32 v93, v127
	v_cvt_f32_f16_e32 v91, v128
	v_cvt_f32_f16_e32 v90, v129
	v_mfma_f32_32x32x16_f16 v[4:19], v[44:47], v[110:113], v[4:19]
	v_mfma_f32_32x32x16_f16 v[36:51], v[56:59], v[36:39], 0
	v_mfma_f32_32x32x16_f16 v[36:51], v[86:89], v[74:77], v[36:51]
	global_load_dword v74, v2, s[34:35]
	s_nop 0
	global_load_dword v2, v2, s[44:45]
	s_mov_b32 s34, 0x3f2aaaab
	v_cvt_f32_f16_e32 v77, v143
	v_cvt_f32_f16_e32 v76, v136
	s_waitcnt vmcnt(2)
	v_mul_f32_e32 v75, 0xbfb8aa3b, v145
	v_mfma_f32_32x32x16_f16 v[52:67], v[56:59], v[52:55], 0
	s_waitcnt vmcnt(1)
	v_add_f32_e32 v20, v20, v74
	v_mfma_f32_32x32x16_f16 v[36:51], v[102:105], v[82:85], v[36:51]
	v_mul_f32_e32 v20, 0xbfb8aa3b, v20
	s_waitcnt vmcnt(0)
	v_add_f32_e32 v4, v4, v2
	v_mul_f32_e32 v4, 0xbfb8aa3b, v4
	v_add_f32_e32 v21, v21, v74
	v_exp_f32_e32 v4, v4
	v_mul_f32_e32 v21, 0xbfb8aa3b, v21
	v_exp_f32_e32 v21, v21
	v_mfma_f32_32x32x16_f16 v[52:67], v[86:89], v[78:81], v[52:67]
	v_add_f32_e32 v4, 1.0, v4
	v_add_f32_e32 v5, v5, v2
	v_add_f32_e32 v21, 1.0, v21
	v_rcp_f32_e32 v21, v21
	v_mul_f32_e32 v5, 0xbfb8aa3b, v5
	v_exp_f32_e32 v5, v5
	v_add_f32_e32 v22, v22, v74
	v_mfma_f32_32x32x16_f16 v[36:51], v[106:109], v[94:97], v[36:51]
	v_exp_f32_e32 v96, v75
	v_mul_f32_e32 v21, 0xc1000000, v21
	v_add_f32_e32 v5, 1.0, v5
	v_rcp_f32_e32 v5, v5
	v_add_f32_e32 v97, 1.0, v96
	v_add_f32_e32 v94, -1.0, v97
	v_sub_f32_e32 v95, v94, v97
	v_add_f32_e32 v95, 1.0, v95
	v_sub_f32_e32 v94, v96, v94
	v_mfma_f32_32x32x16_f16 v[52:67], v[102:105], v[98:101], v[52:67]
	v_add_f32_e32 v98, v94, v95
	v_frexp_mant_f32_e32 v99, v97
	v_cvt_f64_f32_e32 v[94:95], v97
	v_frexp_exp_i32_f64_e32 v94, v[94:95]
	v_cmp_gt_f32_e32 vcc, s34, v99
	s_mov_b32 s34, 0x3f317218
	v_add_f32_e32 v36, v36, v74
	v_subbrev_co_u32_e32 v94, vcc, 0, v94, vcc
	v_sub_u32_e32 v95, 0, v94
	v_ldexp_f32 v97, v97, v95
	v_ldexp_f32 v95, v98, v95
	v_add_f32_e32 v98, -1.0, v97
	v_add_f32_e32 v101, 1.0, v97
	v_add_f32_e32 v99, 1.0, v98
	v_add_f32_e32 v102, -1.0, v101
	v_sub_f32_e32 v99, v97, v99
	v_sub_f32_e32 v97, v97, v102
	v_add_f32_e32 v99, v95, v99
	v_add_f32_e32 v95, v95, v97
	v_add_f32_e32 v97, v101, v95
	v_rcp_f32_e32 v102, v97
	v_add_f32_e32 v100, v98, v99
	v_sub_f32_e32 v98, v100, v98
	v_sub_f32_e32 v98, v99, v98
	v_sub_f32_e32 v99, v97, v101
	v_sub_f32_e32 v95, v95, v99
	v_mul_f32_e32 v99, v100, v102
	v_mul_f32_e32 v101, v97, v99
	v_fma_f32 v103, v99, v97, -v101
	v_fmac_f32_e32 v103, v99, v95
	v_add_f32_e32 v104, v101, v103
	v_sub_f32_e32 v105, v100, v104
	v_sub_f32_e32 v100, v100, v105
	v_sub_f32_e32 v101, v104, v101
	v_sub_f32_e32 v100, v100, v104
	v_add_f32_e32 v98, v98, v100
	v_sub_f32_e32 v100, v101, v103
	v_add_f32_e32 v98, v100, v98
	v_add_f32_e32 v100, v105, v98
	v_mul_f32_e32 v101, v102, v100
	v_mul_f32_e32 v103, v97, v101
	v_fma_f32 v97, v101, v97, -v103
	v_fmac_f32_e32 v97, v101, v95
	v_sub_f32_e32 v95, v105, v100
	v_add_f32_e32 v95, v98, v95
	v_add_f32_e32 v98, v103, v97
	v_sub_f32_e32 v104, v100, v98
	v_sub_f32_e32 v100, v100, v104
	v_sub_f32_e32 v103, v98, v103
	v_sub_f32_e32 v98, v100, v98
	v_add_f32_e32 v95, v95, v98
	v_sub_f32_e32 v97, v103, v97
	v_cvt_f32_i32_e32 v94, v94
	v_add_f32_e32 v95, v97, v95
	v_add_f32_e32 v97, v99, v101
	v_add_f32_e32 v95, v104, v95
	v_sub_f32_e32 v98, v97, v99
	v_mul_f32_e32 v95, v102, v95
	v_sub_f32_e32 v98, v101, v98
	v_add_f32_e32 v95, v98, v95
	v_mul_f32_e32 v101, 0x3f317218, v94
	v_add_f32_e32 v98, v97, v95
	v_fma_f32 v102, v94, s34, -v101
	v_mul_f32_e32 v99, v98, v98
	v_fmac_f32_e32 v102, 0xb102e308, v94
	v_sub_f32_e32 v94, v98, v97
	v_fmamk_f32 v100, v99, 0x3e9b6dac, v201
	v_sub_f32_e32 v94, v95, v94
	v_add_f32_e32 v95, v101, v102
	v_fmaak_f32 v100, v99, v100, 0x3f2aaada
	v_sub_f32_e32 v97, v95, v101
	v_ldexp_f32 v101, v98, 1
	v_mul_f32_e32 v98, v98, v99
	v_mul_f32_e32 v98, v98, v100
	v_add_f32_e32 v99, v101, v98
	v_sub_f32_e32 v100, v99, v101
	v_ldexp_f32 v94, v94, 1
	v_sub_f32_e32 v98, v98, v100
	v_add_f32_e32 v94, v94, v98
	v_add_f32_e32 v98, v99, v94
	v_sub_f32_e32 v99, v98, v99
	v_sub_f32_e32 v94, v94, v99
	v_add_f32_e32 v99, v95, v98
	v_sub_f32_e32 v100, v99, v95
	v_sub_f32_e32 v101, v99, v100
	v_sub_f32_e32 v97, v102, v97
	v_sub_f32_e32 v95, v95, v101
	v_sub_f32_e32 v98, v98, v100
	v_add_f32_e32 v95, v98, v95
	v_add_f32_e32 v98, v97, v94
	v_sub_f32_e32 v100, v98, v97
	v_sub_f32_e32 v101, v98, v100
	v_sub_f32_e32 v97, v97, v101
	v_sub_f32_e32 v94, v94, v100
	v_add_f32_e32 v95, v98, v95
	v_add_f32_e32 v94, v94, v97
	v_add_f32_e32 v97, v99, v95
	v_sub_f32_e32 v98, v97, v99
	v_sub_f32_e32 v95, v95, v98
	v_add_f32_e32 v94, v94, v95
	v_exp_f32_e32 v95, v20
	v_add_f32_e32 v94, v97, v94
	v_cmp_neq_f32_e32 vcc, s40, v96
	v_mul_f32_e32 v36, 0xbfb8aa3b, v36
	v_exp_f32_e32 v36, v36
	v_cndmask_b32_e32 v94, v215, v94, vcc
	v_cmp_ngt_f32_e32 vcc, -1.0, v96
	s_mov_b32 s34, 0x33800000
	v_mfma_f32_32x32x16_f16 v[52:67], v[106:109], v[110:113], v[52:67]
	v_cndmask_b32_e32 v94, v216, v94, vcc
	v_cmp_neq_f32_e32 vcc, -1.0, v96
	v_add_f32_e32 v36, 1.0, v36
	v_rcp_f32_e32 v36, v36
	v_cndmask_b32_e32 v20, v217, v94, vcc
	v_add_f32_e32 v94, 1.0, v95
	v_rcp_f32_e32 v94, v94
	v_cmp_lt_f32_e64 vcc, |v96|, s34
	v_mul_f32_e32 v36, 0xc1000000, v36
	s_nop 2
	v_add_f32_e32 v52, v52, v2
	v_cndmask_b32_e32 v20, v20, v96, vcc
	v_mul_f32_e32 v94, 0xc1000000, v94
	v_mul_f32_e32 v94, v94, v20
	v_mul_f32_e32 v94, 0x3fb8aa3b, v94
	v_exp_f32_e32 v94, v94
	v_rcp_f32_e32 v96, v4
	v_mul_f32_e32 v36, v36, v20
	v_mul_f32_e32 v36, 0x3fb8aa3b, v36
	v_fma_f32 v4, -v94, v94, 1.0
	v_max_f32_e32 v4, 0, v4
	v_sqrt_f32_e32 v97, v4
	v_mul_f32_e32 v52, 0xbfb8aa3b, v52
	v_exp_f32_e32 v36, v36
	v_exp_f32_e32 v52, v52
	v_lshlrev_b32_e32 v4, 2, v116
	v_lshlrev_b32_e32 v95, 14, v115
	v_lshl_or_b32 v4, v114, 10, v4
	v_add3_u32 v4, s51, v95, v4
	v_mul_f32_e32 v95, v96, v97
	v_fma_f32 v96, -v36, v36, 1.0
	v_mul_f32_e32 v21, v21, v20
	v_add_f32_e32 v37, v37, v74
	v_add_f32_e32 v52, 1.0, v52
	v_max_f32_e32 v96, 0, v96
	v_mul_f32_e32 v21, 0x3fb8aa3b, v21
	v_mul_f32_e32 v37, 0xbfb8aa3b, v37
	v_rcp_f32_e32 v52, v52
	v_sqrt_f32_e32 v96, v96
	v_exp_f32_e32 v21, v21
	v_exp_f32_e32 v37, v37
	v_mul_f32_e32 v22, 0xbfb8aa3b, v22
	v_mul_f32_e32 v52, v52, v96
	v_fma_f32 v96, -v21, v21, 1.0
	ds_write2st64_b32 v4, v94, v21 offset1:1
	v_add_f32_e32 v21, 1.0, v37
	v_rcp_f32_e32 v21, v21
	v_add_f32_e32 v37, v53, v2
	v_max_f32_e32 v96, 0, v96
	v_mul_f32_e32 v37, 0xbfb8aa3b, v37
	v_mul_f32_e32 v21, 0xc1000000, v21
	v_mul_f32_e32 v21, v21, v20
	v_mul_f32_e32 v21, 0x3fb8aa3b, v21
	v_exp_f32_e32 v21, v21
	v_sqrt_f32_e32 v96, v96
	v_exp_f32_e32 v37, v37
	v_exp_f32_e32 v22, v22
	v_fma_f32 v53, -v21, v21, 1.0
	v_mul_f32_e32 v5, v5, v96
	v_add_f32_e32 v37, 1.0, v37
	v_max_f32_e32 v53, 0, v53
	v_mul_f32_e32 v95, v95, v146
	v_mul_f32_e32 v5, v5, v147
	v_rcp_f32_e32 v37, v37
	v_sqrt_f32_e32 v53, v53
	v_add_f32_e32 v6, v6, v2
	v_add_f32_e32 v23, v23, v74
	ds_write2st64_b32 v4, v95, v5 offset0:128 offset1:129
	ds_write2st64_b32 v4, v36, v21 offset0:32 offset1:33
	v_add_f32_e32 v21, 1.0, v22
	v_mul_f32_e32 v6, 0xbfb8aa3b, v6
	v_mul_f32_e32 v23, 0xbfb8aa3b, v23
	v_exp_f32_e32 v6, v6
	v_rcp_f32_e32 v21, v21
	v_exp_f32_e32 v23, v23
	v_mul_f32_e32 v5, v37, v53
	v_mul_f32_e32 v52, v52, v121
	v_mul_f32_e32 v5, v5, v122
	ds_write2st64_b32 v4, v52, v5 offset0:160 offset1:161
	v_add_f32_e32 v5, 1.0, v6
	v_mul_f32_e32 v6, 0xc1000000, v21
	v_add_f32_e32 v21, v38, v74
	v_add_f32_e32 v23, 1.0, v23
	v_mul_f32_e32 v21, 0xbfb8aa3b, v21
	v_rcp_f32_e32 v23, v23
	v_exp_f32_e32 v21, v21
	v_mul_f32_e32 v6, v6, v20
	v_mul_f32_e32 v6, 0x3fb8aa3b, v6
	v_mul_f32_e32 v23, 0xc1000000, v23
	v_add_f32_e32 v21, 1.0, v21
	v_mul_f32_e32 v23, v23, v20
	v_rcp_f32_e32 v21, v21
	v_mul_f32_e32 v23, 0x3fb8aa3b, v23
	v_exp_f32_e32 v6, v6
	v_exp_f32_e32 v23, v23
	v_mul_f32_e32 v21, 0xc1000000, v21
	v_mul_f32_e32 v21, v21, v20
	v_fma_f32 v22, -v6, v6, 1.0
	ds_write2st64_b32 v4, v6, v23 offset0:2 offset1:3
	v_add_f32_e32 v6, v39, v74
	v_add_f32_e32 v36, v54, v2
	v_mul_f32_e32 v21, 0x3fb8aa3b, v21
	v_mul_f32_e32 v6, 0xbfb8aa3b, v6
	v_mul_f32_e32 v36, 0xbfb8aa3b, v36
	v_exp_f32_e32 v21, v21
	v_exp_f32_e32 v6, v6
	v_exp_f32_e32 v36, v36
	v_add_f32_e32 v7, v7, v2
	v_fma_f32 v37, -v21, v21, 1.0
	v_mul_f32_e32 v7, 0xbfb8aa3b, v7
	v_add_f32_e32 v6, 1.0, v6
	v_max_f32_e32 v22, 0, v22
	v_add_f32_e32 v36, 1.0, v36
	v_max_f32_e32 v37, 0, v37
	v_exp_f32_e32 v7, v7
	v_rcp_f32_e32 v6, v6
	v_rcp_f32_e32 v5, v5
	v_sqrt_f32_e32 v22, v22
	v_rcp_f32_e32 v36, v36
	v_sqrt_f32_e32 v37, v37
	v_fma_f32 v23, -v23, v23, 1.0
	v_add_f32_e32 v7, 1.0, v7
	v_max_f32_e32 v23, 0, v23
	v_mul_f32_e32 v6, 0xc1000000, v6
	v_mul_f32_e32 v5, v5, v22
	v_mul_f32_e32 v22, v36, v37
	v_rcp_f32_e32 v7, v7
	v_sqrt_f32_e32 v23, v23
	v_add_f32_e32 v36, v55, v2
	v_mul_f32_e32 v6, v6, v20
	v_mul_f32_e32 v36, 0xbfb8aa3b, v36
	v_mul_f32_e32 v6, 0x3fb8aa3b, v6
	v_exp_f32_e32 v36, v36
	v_exp_f32_e32 v6, v6
	v_mul_f32_e32 v7, v7, v23
	v_mul_f32_e32 v5, v5, v148
	v_mul_f32_e32 v7, v7, v149
	v_add_f32_e32 v23, 1.0, v36
	v_fma_f32 v36, -v6, v6, 1.0
	ds_write2st64_b32 v4, v5, v7 offset0:130 offset1:131
	ds_write2st64_b32 v4, v21, v6 offset0:34 offset1:35
	v_add_f32_e32 v6, v24, v74
	v_mul_f32_e32 v6, 0xbfb8aa3b, v6
	v_exp_f32_e32 v6, v6
	v_max_f32_e32 v36, 0, v36
	v_rcp_f32_e32 v23, v23
	v_sqrt_f32_e32 v36, v36
	v_add_f32_e32 v6, 1.0, v6
	v_rcp_f32_e32 v6, v6
	v_add_f32_e32 v7, v8, v2
	v_mul_f32_e32 v7, 0xbfb8aa3b, v7
	v_exp_f32_e32 v7, v7
	v_mul_f32_e32 v6, 0xc1000000, v6
	v_mul_f32_e32 v6, v6, v20
	v_mul_f32_e32 v6, 0x3fb8aa3b, v6
	v_exp_f32_e32 v6, v6
	v_mul_f32_e32 v5, v23, v36
	v_mul_f32_e32 v22, v22, v123
	v_mul_f32_e32 v5, v5, v124
	v_fma_f32 v8, -v6, v6, 1.0
	v_add_f32_e32 v21, v56, v2
	ds_write2st64_b32 v4, v22, v5 offset0:162 offset1:163
	v_add_f32_e32 v5, 1.0, v7
	v_max_f32_e32 v8, 0, v8
	v_mul_f32_e32 v21, 0xbfb8aa3b, v21
	v_rcp_f32_e32 v5, v5
	v_sqrt_f32_e32 v8, v8
	v_exp_f32_e32 v21, v21
	v_add_f32_e32 v9, v9, v2
	v_mul_f32_e32 v9, 0xbfb8aa3b, v9
	v_mul_f32_e32 v5, v5, v8
	v_add_f32_e32 v8, 1.0, v21
	v_add_f32_e32 v21, v25, v74
	v_mul_f32_e32 v21, 0xbfb8aa3b, v21
	v_exp_f32_e32 v21, v21
	v_exp_f32_e32 v9, v9
	v_add_f32_e32 v7, v40, v74
	v_mul_f32_e32 v7, 0xbfb8aa3b, v7
	v_add_f32_e32 v21, 1.0, v21
	v_rcp_f32_e32 v21, v21
	v_add_f32_e32 v9, 1.0, v9
	v_rcp_f32_e32 v9, v9
	v_exp_f32_e32 v7, v7
	v_mul_f32_e32 v21, 0xc1000000, v21
	v_mul_f32_e32 v21, v21, v20
	v_mul_f32_e32 v21, 0x3fb8aa3b, v21
	v_exp_f32_e32 v21, v21
	v_add_f32_e32 v7, 1.0, v7
	v_rcp_f32_e32 v7, v7
	v_mul_f32_e32 v5, v5, v117
	v_fma_f32 v23, -v21, v21, 1.0
	v_max_f32_e32 v23, 0, v23
	v_sqrt_f32_e32 v23, v23
	ds_write2st64_b32 v4, v6, v21 offset0:8 offset1:9
	v_mul_f32_e32 v7, 0xc1000000, v7
	v_mul_f32_e32 v7, v7, v20
	v_mul_f32_e32 v6, v9, v23
	v_add_f32_e32 v9, v41, v74
	v_mul_f32_e32 v9, 0xbfb8aa3b, v9
	v_exp_f32_e32 v9, v9
	v_mul_f32_e32 v6, v6, v118
	ds_write2st64_b32 v4, v5, v6 offset0:136 offset1:137
	v_mul_f32_e32 v7, 0x3fb8aa3b, v7
	v_add_f32_e32 v9, 1.0, v9
	v_rcp_f32_e32 v9, v9
	v_exp_f32_e32 v7, v7
	v_add_f32_e32 v21, v57, v2
	v_mul_f32_e32 v21, 0xbfb8aa3b, v21
	v_mul_f32_e32 v6, 0xc1000000, v9
	v_mul_f32_e32 v6, v6, v20
	v_add_f32_e32 v9, v26, v74
	v_mul_f32_e32 v6, 0x3fb8aa3b, v6
	v_mul_f32_e32 v9, 0xbfb8aa3b, v9
	v_exp_f32_e32 v6, v6
	v_exp_f32_e32 v9, v9
	v_fma_f32 v22, -v7, v7, 1.0
	v_exp_f32_e32 v21, v21
	ds_write2st64_b32 v4, v7, v6 offset0:40 offset1:41
	v_add_f32_e32 v7, 1.0, v9
	v_rcp_f32_e32 v7, v7
	v_fma_f32 v6, -v6, v6, 1.0
	v_add_f32_e32 v5, 1.0, v21
	v_max_f32_e32 v6, 0, v6
	v_mul_f32_e32 v7, 0xc1000000, v7
	v_mul_f32_e32 v7, v7, v20
	v_add_f32_e32 v9, v10, v2
	v_mul_f32_e32 v7, 0x3fb8aa3b, v7
	v_rcp_f32_e32 v5, v5
	v_mul_f32_e32 v9, 0xbfb8aa3b, v9
	v_exp_f32_e32 v7, v7
	v_sqrt_f32_e32 v6, v6
	v_exp_f32_e32 v9, v9
	v_max_f32_e32 v22, 0, v22
	v_rcp_f32_e32 v8, v8
	v_sqrt_f32_e32 v22, v22
	v_fma_f32 v10, -v7, v7, 1.0
	v_mul_f32_e32 v5, v5, v6
	v_add_f32_e32 v6, v42, v74
	v_add_f32_e32 v9, 1.0, v9
	v_max_f32_e32 v10, 0, v10
	v_mul_f32_e32 v6, 0xbfb8aa3b, v6
	v_rcp_f32_e32 v9, v9
	v_sqrt_f32_e32 v10, v10
	v_exp_f32_e32 v6, v6
	v_mul_f32_e32 v8, v8, v22
	v_mul_f32_e32 v8, v8, v125
	v_mul_f32_e32 v5, v5, v126
	ds_write2st64_b32 v4, v8, v5 offset0:168 offset1:169
	v_mul_f32_e32 v5, v9, v10
	v_add_f32_e32 v6, 1.0, v6
	v_add_f32_e32 v9, v27, v74
	v_rcp_f32_e32 v6, v6
	v_mul_f32_e32 v9, 0xbfb8aa3b, v9
	v_exp_f32_e32 v9, v9
	v_add_f32_e32 v8, v58, v2
	v_mul_f32_e32 v6, 0xc1000000, v6
	v_mul_f32_e32 v6, v6, v20
	v_add_f32_e32 v9, 1.0, v9
	v_mul_f32_e32 v6, 0x3fb8aa3b, v6
	v_rcp_f32_e32 v9, v9
	v_mul_f32_e32 v8, 0xbfb8aa3b, v8
	v_exp_f32_e32 v6, v6
	v_exp_f32_e32 v8, v8
	v_mul_f32_e32 v9, 0xc1000000, v9
	v_add_f32_e32 v11, v11, v2
	v_fma_f32 v10, -v6, v6, 1.0
	v_mul_f32_e32 v9, v9, v20
	v_add_f32_e32 v21, v43, v74
	v_add_f32_e32 v8, 1.0, v8
	v_max_f32_e32 v10, 0, v10
	v_mul_f32_e32 v11, 0xbfb8aa3b, v11
	v_mul_f32_e32 v9, 0x3fb8aa3b, v9
	v_mul_f32_e32 v21, 0xbfb8aa3b, v21
	v_rcp_f32_e32 v8, v8
	v_sqrt_f32_e32 v10, v10
	v_exp_f32_e32 v11, v11
	v_exp_f32_e32 v9, v9
	v_exp_f32_e32 v21, v21
	v_mul_f32_e32 v8, v8, v10
	v_add_f32_e32 v10, 1.0, v11
	v_fma_f32 v11, -v9, v9, 1.0
	ds_write2st64_b32 v4, v7, v9 offset0:10 offset1:11
	v_add_f32_e32 v9, 1.0, v21
	v_rcp_f32_e32 v9, v9
	v_max_f32_e32 v11, 0, v11
	v_rcp_f32_e32 v10, v10
	v_sqrt_f32_e32 v11, v11
	v_mul_f32_e32 v9, 0xc1000000, v9
	v_mul_f32_e32 v9, v9, v20
	v_mul_f32_e32 v9, 0x3fb8aa3b, v9
	v_mul_f32_e32 v7, v10, v11
	v_add_f32_e32 v10, v59, v2
	v_mul_f32_e32 v10, 0xbfb8aa3b, v10
	v_exp_f32_e32 v9, v9
	v_exp_f32_e32 v10, v10
	v_mul_f32_e32 v5, v5, v119
	v_mul_f32_e32 v7, v7, v92
	v_fma_f32 v11, -v9, v9, 1.0
	v_add_f32_e32 v10, 1.0, v10
	v_max_f32_e32 v11, 0, v11
	v_rcp_f32_e32 v10, v10
	v_sqrt_f32_e32 v11, v11
	ds_write2st64_b32 v4, v5, v7 offset0:138 offset1:139
	ds_write2st64_b32 v4, v6, v9 offset0:42 offset1:43
	v_add_f32_e32 v7, v12, v2
	v_mul_f32_e32 v7, 0xbfb8aa3b, v7
	v_exp_f32_e32 v7, v7
	v_mul_f32_e32 v5, v10, v11
	v_mul_f32_e32 v8, v8, v93
	v_mul_f32_e32 v5, v5, v91
	v_add_f32_e32 v21, v28, v74
	ds_write2st64_b32 v4, v8, v5 offset0:170 offset1:171
	v_add_f32_e32 v5, 1.0, v7
	v_add_f32_e32 v7, v44, v74
	v_mul_f32_e32 v21, 0xbfb8aa3b, v21
	v_mul_f32_e32 v7, 0xbfb8aa3b, v7
	v_exp_f32_e32 v21, v21
	v_exp_f32_e32 v7, v7
	v_add_f32_e32 v9, v60, v2
	v_mul_f32_e32 v9, 0xbfb8aa3b, v9
	v_add_f32_e32 v6, 1.0, v21
	v_add_f32_e32 v7, 1.0, v7
	v_rcp_f32_e32 v6, v6
	v_rcp_f32_e32 v7, v7
	v_exp_f32_e32 v9, v9
	v_add_f32_e32 v11, v29, v74
	v_mul_f32_e32 v6, 0xc1000000, v6
	v_mul_f32_e32 v7, 0xc1000000, v7
	v_mul_f32_e32 v6, v6, v20
	v_mul_f32_e32 v7, v7, v20
	v_mul_f32_e32 v6, 0x3fb8aa3b, v6
	v_mul_f32_e32 v7, 0x3fb8aa3b, v7
	v_exp_f32_e32 v6, v6
	v_exp_f32_e32 v7, v7
	v_add_f32_e32 v9, 1.0, v9
	v_mul_f32_e32 v11, 0xbfb8aa3b, v11
	v_fma_f32 v8, -v6, v6, 1.0
	v_fma_f32 v10, -v7, v7, 1.0
	v_max_f32_e32 v8, 0, v8
	v_max_f32_e32 v10, 0, v10
	v_rcp_f32_e32 v5, v5
	v_sqrt_f32_e32 v8, v8
	v_rcp_f32_e32 v9, v9
	v_sqrt_f32_e32 v10, v10
	v_exp_f32_e32 v11, v11
	v_mul_f32_e32 v5, v5, v8
	v_cvt_f32_f16_e32 v88, v130
	v_mul_f32_e32 v8, v9, v10
	v_add_f32_e32 v9, 1.0, v11
	v_rcp_f32_e32 v9, v9
	v_add_f32_e32 v10, v13, v2
	v_mul_f32_e32 v10, 0xbfb8aa3b, v10
	v_exp_f32_e32 v10, v10
	v_mul_f32_e32 v9, 0xc1000000, v9
	v_mul_f32_e32 v9, v9, v20
	v_mul_f32_e32 v9, 0x3fb8aa3b, v9
	v_exp_f32_e32 v9, v9
	v_add_f32_e32 v10, 1.0, v10
	v_rcp_f32_e32 v10, v10
	v_add_f32_e32 v11, v61, v2
	ds_write2st64_b32 v4, v6, v9 offset0:16 offset1:17
	v_add_f32_e32 v6, v45, v74
	v_mul_f32_e32 v6, 0xbfb8aa3b, v6
	v_exp_f32_e32 v6, v6
	v_fma_f32 v9, -v9, v9, 1.0
	v_max_f32_e32 v9, 0, v9
	v_sqrt_f32_e32 v9, v9
	v_add_f32_e32 v6, 1.0, v6
	v_rcp_f32_e32 v6, v6
	v_mul_f32_e32 v11, 0xbfb8aa3b, v11
	v_exp_f32_e32 v11, v11
	v_mul_f32_e32 v9, v10, v9
	v_mul_f32_e32 v6, 0xc1000000, v6
	v_mul_f32_e32 v6, v6, v20
	v_mul_f32_e32 v6, 0x3fb8aa3b, v6
	v_exp_f32_e32 v6, v6
	v_mul_f32_e32 v5, v5, v90
	v_mul_f32_e32 v9, v9, v88
	v_add_f32_e32 v10, 1.0, v11
	v_fma_f32 v11, -v6, v6, 1.0
	ds_write2st64_b32 v4, v5, v9 offset0:144 offset1:145
	ds_write2st64_b32 v4, v7, v6 offset0:48 offset1:49
	v_add_f32_e32 v6, v30, v74
	v_mul_f32_e32 v6, 0xbfb8aa3b, v6
	v_exp_f32_e32 v6, v6
	v_max_f32_e32 v11, 0, v11
	v_rcp_f32_e32 v10, v10
	v_sqrt_f32_e32 v11, v11
	v_add_f32_e32 v6, 1.0, v6
	v_rcp_f32_e32 v6, v6
	v_cvt_f32_f16_e32 v89, v137
	v_cvt_f32_f16_e32 v87, v138
	v_add_f32_e32 v7, v14, v2
	v_mul_f32_e32 v6, 0xc1000000, v6
	v_mul_f32_e32 v6, v6, v20
	v_mul_f32_e32 v6, 0x3fb8aa3b, v6
	v_mul_f32_e32 v7, 0xbfb8aa3b, v7
	v_exp_f32_e32 v6, v6
	v_exp_f32_e32 v7, v7
	v_mul_f32_e32 v5, v10, v11
	v_mul_f32_e32 v8, v8, v89
	v_mul_f32_e32 v5, v5, v87
	ds_write2st64_b32 v4, v8, v5 offset0:176 offset1:177
	v_fma_f32 v8, -v6, v6, 1.0
	v_add_f32_e32 v9, v62, v2
	v_add_f32_e32 v5, 1.0, v7
	v_max_f32_e32 v8, 0, v8
	v_mul_f32_e32 v9, 0xbfb8aa3b, v9
	v_rcp_f32_e32 v5, v5
	v_sqrt_f32_e32 v8, v8
	v_exp_f32_e32 v9, v9
	v_add_f32_e32 v7, v46, v74
	v_mul_f32_e32 v7, 0xbfb8aa3b, v7
	v_mul_f32_e32 v5, v5, v8
	v_add_f32_e32 v8, 1.0, v9
	v_add_f32_e32 v9, v31, v74
	v_mul_f32_e32 v9, 0xbfb8aa3b, v9
	v_exp_f32_e32 v9, v9
	v_exp_f32_e32 v7, v7
	v_add_f32_e32 v11, v15, v2
	v_mul_f32_e32 v11, 0xbfb8aa3b, v11
	v_add_f32_e32 v9, 1.0, v9
	v_rcp_f32_e32 v9, v9
	v_exp_f32_e32 v11, v11
	v_add_f32_e32 v7, 1.0, v7
	v_rcp_f32_e32 v7, v7
	v_mul_f32_e32 v9, 0xc1000000, v9
	v_mul_f32_e32 v9, v9, v20
	v_mul_f32_e32 v9, 0x3fb8aa3b, v9
	v_exp_f32_e32 v9, v9
	v_add_f32_e32 v11, 1.0, v11
	v_rcp_f32_e32 v11, v11
	v_cvt_f32_f16_e32 v86, v131
	v_fma_f32 v12, -v9, v9, 1.0
	ds_write2st64_b32 v4, v6, v9 offset0:18 offset1:19
	v_add_f32_e32 v9, v47, v74
	v_mul_f32_e32 v9, 0xbfb8aa3b, v9
	v_exp_f32_e32 v9, v9
	v_max_f32_e32 v12, 0, v12
	v_sqrt_f32_e32 v12, v12
	v_cvt_f32_f16_e32 v84, v132
	v_mul_f32_e32 v7, 0xc1000000, v7
	v_add_f32_e32 v9, 1.0, v9
	v_mul_f32_e32 v7, v7, v20
	v_rcp_f32_e32 v9, v9
	v_mul_f32_e32 v7, 0x3fb8aa3b, v7
	v_exp_f32_e32 v7, v7
	v_mul_f32_e32 v6, v11, v12
	v_mul_f32_e32 v5, v5, v86
	v_mul_f32_e32 v6, v6, v84
	ds_write2st64_b32 v4, v5, v6 offset0:146 offset1:147
	v_mul_f32_e32 v6, 0xc1000000, v9
	v_mul_f32_e32 v6, v6, v20
	v_add_f32_e32 v9, v32, v74
	v_fma_f32 v10, -v7, v7, 1.0
	v_mul_f32_e32 v6, 0x3fb8aa3b, v6
	v_mul_f32_e32 v9, 0xbfb8aa3b, v9
	v_max_f32_e32 v10, 0, v10
	v_exp_f32_e32 v6, v6
	v_exp_f32_e32 v9, v9
	v_rcp_f32_e32 v8, v8
	v_sqrt_f32_e32 v10, v10
	ds_write2st64_b32 v4, v7, v6 offset0:50 offset1:51
	v_add_f32_e32 v7, 1.0, v9
	v_rcp_f32_e32 v7, v7
	v_mul_f32_e32 v8, v8, v10
	v_add_f32_e32 v10, v63, v2
	v_mul_f32_e32 v10, 0xbfb8aa3b, v10
	v_exp_f32_e32 v10, v10
	v_mul_f32_e32 v7, 0xc1000000, v7
	v_fma_f32 v6, -v6, v6, 1.0
	v_mul_f32_e32 v7, v7, v20
	v_add_f32_e32 v5, 1.0, v10
	v_max_f32_e32 v6, 0, v6
	v_add_f32_e32 v9, v16, v2
	v_mul_f32_e32 v7, 0x3fb8aa3b, v7
	v_rcp_f32_e32 v5, v5
	v_mul_f32_e32 v9, 0xbfb8aa3b, v9
	v_exp_f32_e32 v7, v7
	v_sqrt_f32_e32 v6, v6
	v_exp_f32_e32 v9, v9
	v_cvt_f32_f16_e32 v85, v139
	v_fma_f32 v10, -v7, v7, 1.0
	v_mul_f32_e32 v5, v5, v6
	v_add_f32_e32 v6, v48, v74
	v_cvt_f32_f16_e32 v83, v140
	v_add_f32_e32 v9, 1.0, v9
	v_max_f32_e32 v10, 0, v10
	v_mul_f32_e32 v6, 0xbfb8aa3b, v6
	v_rcp_f32_e32 v9, v9
	v_sqrt_f32_e32 v10, v10
	v_exp_f32_e32 v6, v6
	v_mul_f32_e32 v8, v8, v85
	v_mul_f32_e32 v5, v5, v83
	ds_write2st64_b32 v4, v8, v5 offset0:178 offset1:179
	v_mul_f32_e32 v5, v9, v10
	v_add_f32_e32 v6, 1.0, v6
	v_add_f32_e32 v9, v33, v74
	v_rcp_f32_e32 v6, v6
	v_mul_f32_e32 v9, 0xbfb8aa3b, v9
	v_exp_f32_e32 v9, v9
	v_add_f32_e32 v8, v64, v2
	v_mul_f32_e32 v6, 0xc1000000, v6
	v_mul_f32_e32 v6, v6, v20
	v_add_f32_e32 v9, 1.0, v9
	v_mul_f32_e32 v6, 0x3fb8aa3b, v6
	v_rcp_f32_e32 v9, v9
	v_mul_f32_e32 v8, 0xbfb8aa3b, v8
	v_exp_f32_e32 v6, v6
	v_exp_f32_e32 v8, v8
	v_mul_f32_e32 v9, 0xc1000000, v9
	v_add_f32_e32 v11, v17, v2
	v_fma_f32 v10, -v6, v6, 1.0
	v_mul_f32_e32 v9, v9, v20
	v_add_f32_e32 v12, v49, v74
	v_add_f32_e32 v8, 1.0, v8
	v_max_f32_e32 v10, 0, v10
	v_mul_f32_e32 v11, 0xbfb8aa3b, v11
	v_mul_f32_e32 v9, 0x3fb8aa3b, v9
	v_mul_f32_e32 v12, 0xbfb8aa3b, v12
	v_rcp_f32_e32 v8, v8
	v_sqrt_f32_e32 v10, v10
	v_exp_f32_e32 v11, v11
	v_exp_f32_e32 v9, v9
	v_exp_f32_e32 v12, v12
	v_mul_f32_e32 v8, v8, v10
	v_add_f32_e32 v10, 1.0, v11
	v_fma_f32 v11, -v9, v9, 1.0
	ds_write2st64_b32 v4, v7, v9 offset0:24 offset1:25
	v_add_f32_e32 v9, 1.0, v12
	v_rcp_f32_e32 v9, v9
	v_max_f32_e32 v11, 0, v11
	v_rcp_f32_e32 v10, v10
	v_sqrt_f32_e32 v11, v11
	v_mul_f32_e32 v9, 0xc1000000, v9
	v_mul_f32_e32 v9, v9, v20
	v_mul_f32_e32 v9, 0x3fb8aa3b, v9
	v_mul_f32_e32 v7, v10, v11
	v_add_f32_e32 v10, v65, v2
	v_mul_f32_e32 v10, 0xbfb8aa3b, v10
	v_exp_f32_e32 v9, v9
	v_cvt_f32_f16_e32 v82, v133
	v_cvt_f32_f16_e32 v80, v134
	v_exp_f32_e32 v10, v10
	v_fma_f32 v11, -v9, v9, 1.0
	v_mul_f32_e32 v5, v5, v82
	v_mul_f32_e32 v7, v7, v80
	v_add_f32_e32 v10, 1.0, v10
	v_max_f32_e32 v11, 0, v11
	v_rcp_f32_e32 v10, v10
	v_sqrt_f32_e32 v11, v11
	ds_write2st64_b32 v4, v5, v7 offset0:152 offset1:153
	ds_write2st64_b32 v4, v6, v9 offset0:56 offset1:57
	v_add_f32_e32 v7, v18, v2
	v_cvt_f32_f16_e32 v81, v141
	v_cvt_f32_f16_e32 v79, v142
	v_mul_f32_e32 v7, 0xbfb8aa3b, v7
	v_exp_f32_e32 v7, v7
	v_mul_f32_e32 v5, v10, v11
	v_mul_f32_e32 v8, v8, v81
	v_mul_f32_e32 v5, v5, v79
	v_add_f32_e32 v12, v34, v74
	ds_write2st64_b32 v4, v8, v5 offset0:184 offset1:185
	v_add_f32_e32 v5, 1.0, v7
	v_add_f32_e32 v7, v50, v74
	v_mul_f32_e32 v12, 0xbfb8aa3b, v12
	v_mul_f32_e32 v7, 0xbfb8aa3b, v7
	v_exp_f32_e32 v12, v12
	v_exp_f32_e32 v7, v7
	v_add_f32_e32 v9, v66, v2
	v_mul_f32_e32 v9, 0xbfb8aa3b, v9
	v_add_f32_e32 v6, 1.0, v12
	v_add_f32_e32 v7, 1.0, v7
	v_rcp_f32_e32 v6, v6
	v_rcp_f32_e32 v7, v7
	v_exp_f32_e32 v9, v9
	v_add_f32_e32 v11, v35, v74
	v_mul_f32_e32 v6, 0xc1000000, v6
	v_mul_f32_e32 v7, 0xc1000000, v7
	v_mul_f32_e32 v6, v6, v20
	v_mul_f32_e32 v7, v7, v20
	v_mul_f32_e32 v6, 0x3fb8aa3b, v6
	v_mul_f32_e32 v7, 0x3fb8aa3b, v7
	v_exp_f32_e32 v6, v6
	v_exp_f32_e32 v7, v7
	v_add_f32_e32 v9, 1.0, v9
	v_mul_f32_e32 v11, 0xbfb8aa3b, v11
	v_fma_f32 v8, -v6, v6, 1.0
	v_fma_f32 v10, -v7, v7, 1.0
	v_max_f32_e32 v8, 0, v8
	v_max_f32_e32 v10, 0, v10
	v_rcp_f32_e32 v5, v5
	v_sqrt_f32_e32 v8, v8
	v_rcp_f32_e32 v9, v9
	v_sqrt_f32_e32 v10, v10
	v_exp_f32_e32 v11, v11
	v_mul_f32_e32 v5, v5, v8
	v_cvt_f32_f16_e32 v78, v135
	v_mul_f32_e32 v8, v9, v10
	v_add_f32_e32 v9, 1.0, v11
	v_rcp_f32_e32 v9, v9
	v_add_f32_e32 v10, v19, v2
	v_mul_f32_e32 v10, 0xbfb8aa3b, v10
	v_exp_f32_e32 v10, v10
	v_mul_f32_e32 v9, 0xc1000000, v9
	v_mul_f32_e32 v9, v9, v20
	v_mul_f32_e32 v9, 0x3fb8aa3b, v9
	v_exp_f32_e32 v9, v9
	v_add_f32_e32 v10, 1.0, v10
	v_add_f32_e32 v2, v67, v2
	v_rcp_f32_e32 v10, v10
	ds_write2st64_b32 v4, v6, v9 offset0:26 offset1:27
	v_add_f32_e32 v6, v51, v74
	v_mul_f32_e32 v6, 0xbfb8aa3b, v6
	v_exp_f32_e32 v6, v6
	v_fma_f32 v9, -v9, v9, 1.0
	v_max_f32_e32 v9, 0, v9
	v_sqrt_f32_e32 v9, v9
	v_add_f32_e32 v6, 1.0, v6
	v_rcp_f32_e32 v6, v6
	v_mul_f32_e32 v2, 0xbfb8aa3b, v2
	v_exp_f32_e32 v2, v2
	v_mul_f32_e32 v9, v10, v9
	v_mul_f32_e32 v6, 0xc1000000, v6
	v_mul_f32_e32 v6, v6, v20
	v_mul_f32_e32 v6, 0x3fb8aa3b, v6
	v_exp_f32_e32 v6, v6
	v_add_f32_e32 v2, 1.0, v2
	v_rcp_f32_e32 v2, v2
	v_cvt_f32_f16_e32 v75, v144
	v_fma_f32 v10, -v6, v6, 1.0
	v_max_f32_e32 v10, 0, v10
	v_sqrt_f32_e32 v10, v10
	v_mul_f32_e32 v5, v5, v78
	v_mul_f32_e32 v8, v8, v77
	v_mul_f32_e32 v9, v9, v76
	v_mul_f32_e32 v2, v2, v10
	v_mul_f32_e32 v2, v2, v75
	ds_write2st64_b32 v4, v5, v9 offset0:154 offset1:155
	ds_write2st64_b32 v4, v7, v6 offset0:58 offset1:59
	ds_write2st64_b32 v4, v8, v2 offset0:186 offset1:187
	s_waitcnt lgkmcnt(0)
	s_barrier
	s_and_saveexec_b64 s[34:35], s[42:43]
	s_cbranch_execz .LBB0_913
	v_lshlrev_b32_e32 v2, 14, v70
	v_lshlrev_b32_e32 v4, 2, v71
	v_add3_u32 v2, s51, v2, v4
	v_cmp_gt_u32_e64 s[42:43], 64, v72
	v_cmp_lt_u32_e32 vcc, 63, v72
	s_mov_b32 s44, 56
	s_mov_b32 s45, 0

.LBB0_1099:
	s_and_b64 vcc, exec, s[24:25]
	s_cbranch_vccz .LBB0_1115
	s_ashr_i32 s36, s34, 3
	v_mov_b32_e32 v68, v200
	s_lshl_b32 s31, s36, 6
	s_lshl_b32 s24, s34, 3
	s_and_b32 s28, s34, 7
	s_and_b32 s24, s24, 0xffffff00
	s_and_b32 s25, s31, 0xfffff000
	s_load_dwordx2 s[26:27], s[22:23], 0xa0
	s_cmp_lt_i32 s36, 64
	v_lshlrev_b32_e32 v24, 4, v68
	s_cselect_b32 s30, 0x100, s38
	s_cselect_b32 s29, s24, s25
	v_and_b32_e32 v22, 48, v24
	s_lshl_b32 s37, s28, 6
	v_or_b32_e32 v2, s37, v22
	v_lshlrev_b32_e32 v0, 2, v2
	s_load_dwordx2 s[24:25], s[22:23], 0x110
	s_waitcnt lgkmcnt(0)
	global_load_dwordx4 v[8:11], v0, s[26:27] offset:48
	global_load_dwordx4 v[4:7], v0, s[26:27] offset:32
	global_load_dwordx4 v[16:19], v0, s[26:27] offset:16
	global_load_dwordx4 v[12:15], v0, s[26:27]
	s_lshl_b32 s27, s28, 13
	s_add_u32 s26, s24, s27
	s_addc_u32 s27, s25, 0
	s_add_u32 s26, s26, 0x2d00000
	s_addc_u32 s27, s27, 0
	v_bfe_u32 v174, v200, 3, 5
	v_and_b32_e32 v175, 7, v200
	v_lshlrev_b32_e32 v174, 7, v174
	v_lshl_or_b32 v174, v175, 4, v174
	global_load_dwordx4 v[184:187], v174, s[26:27]
	v_add_u32_e32 v175, 0x1000, v174
	global_load_dwordx4 v[188:191], v175, s[26:27]
	v_add_u32_e32 v176, 0x10000, v174
	global_load_dwordx4 v[192:195], v176, s[26:27]
	v_add_u32_e32 v175, 0x11000, v174
	global_load_dwordx4 v[196:199], v175, s[26:27]
	v_add_u32_e32 v176, 0x20000, v174
	global_load_dwordx4 v[238:241], v176, s[26:27]
	v_add_u32_e32 v175, 0x21000, v174
	global_load_dwordx4 v[242:245], v175, s[26:27]
	v_add_u32_e32 v176, 0x30000, v174
	global_load_dwordx4 v[246:249], v176, s[26:27]
	v_add_u32_e32 v175, 0x31000, v174
	global_load_dwordx4 v[250:253], v175, s[26:27]
	v_bfe_u32 v23, v68, 2, 6
	v_or_b32_e32 v25, s31, v23
	s_add_i32 s30, s29, s30
	v_add_u32_e32 v1, -2, v25
	v_lshlrev_b32_e32 v2, 1, v2
	v_lshl_add_u64 v[20:21], s[24:25], 0, v[2:3]
	s_mov_b64 s[26:27], 0xaa08000
	v_cmp_le_i32_e32 vcc, s29, v1
	v_cmp_gt_i32_e64 s[42:43], s30, v1
	v_lshl_add_u64 v[20:21], v[20:21], 0, s[26:27]
	s_load_dwordx2 s[42:43], s[22:23], 0x98
	v_mov_b32_e32 v74, 0
	v_mov_b32_e32 v75, 0
	v_mov_b32_e32 v76, 0
	v_mov_b32_e32 v77, 0
	v_mov_b32_e32 v78, 0
	v_mov_b32_e32 v79, 0
	v_mov_b32_e32 v80, 0
	v_mov_b32_e32 v81, 0
	v_mov_b32_e32 v82, 0
	v_mov_b32_e32 v83, 0
	v_mov_b32_e32 v84, 0
	v_mov_b32_e32 v85, 0
	v_mov_b32_e32 v86, 0
	v_mov_b32_e32 v87, 0
	v_mov_b32_e32 v88, 0
	v_mov_b32_e32 v89, 0
	v_mov_b32_e32 v90, 0
	v_mov_b32_e32 v91, 0
	v_mov_b32_e32 v92, 0
	v_mov_b32_e32 v93, 0
	v_mov_b32_e32 v94, 0
	v_mov_b32_e32 v95, 0
	v_mov_b32_e32 v96, 0
	v_mov_b32_e32 v97, 0
	v_mov_b32_e32 v98, 0
	v_mov_b32_e32 v99, 0
	v_mov_b32_e32 v100, 0
	v_mov_b32_e32 v101, 0
	v_mov_b32_e32 v102, 0
	v_mov_b32_e32 v103, 0
	v_mov_b32_e32 v104, 0
	v_mov_b32_e32 v105, 0
	v_add_u32_e32 v108, 0x1000, v0
	v_add_u32_e32 v109, -2, v25
	v_cmp_le_i32_e32 vcc, s29, v109
	v_cmp_gt_i32_e64 s[26:27], s30, v109
	s_and_b64 vcc, vcc, s[26:27]
	s_and_saveexec_b64 s[26:27], vcc
	s_cbranch_execz .Lcva_0
	v_mad_i64_i32 v[106:107], vcc, v109, s97, v[20:21]
	global_load_dwordx4 v[74:77], v[106:107], off
	global_load_dwordx4 v[78:81], v[106:107], off offset:16

.LBB0_1108:
	s_or_b64 exec, exec, s[26:27]
	s_lshl_b32 s26, s28, 13
	s_add_u32 s28, s24, s26
	v_lshrrev_b32_sdwa v56, v218, v68 dst_sel:DWORD dst_unused:UNUSED_PAD src0_sel:DWORD src1_sel:BYTE_0
	s_addc_u32 s29, s25, 0
	s_add_u32 s26, s28, 0x2d00000
	v_lshlrev_b32_e32 v2, 7, v56
	s_addc_u32 s27, s29, 0
	v_or_b32_e32 v48, 0x1000, v2
	v_mov_b32_e32 v49, v3
	v_and_b32_e32 v0, 0x70, v24
	v_lshl_add_u64 v[20:21], s[26:27], 0, v[2:3]
	v_mov_b32_e32 v1, v3
	v_lshl_add_u64 v[24:25], s[26:27], 0, v[48:49]
	s_add_u32 s26, s28, 0x2d10000
	v_lshl_add_u64 v[20:21], v[20:21], 0, v[0:1]
	v_lshl_add_u64 v[28:29], v[24:25], 0, v[0:1]
	s_addc_u32 s27, s29, 0
	s_nop 0
	s_nop 0
	s_nop 0
	v_lshl_add_u64 v[20:21], s[26:27], 0, v[2:3]
	v_lshl_add_u64 v[32:33], s[26:27], 0, v[48:49]
	s_add_u32 s26, s28, 0x2d20000
	v_lshl_add_u64 v[20:21], v[20:21], 0, v[0:1]
	v_lshl_add_u64 v[36:37], v[32:33], 0, v[0:1]
	s_addc_u32 s27, s29, 0
	s_nop 0
	s_nop 0
	s_nop 0
	v_lshl_add_u64 v[20:21], s[26:27], 0, v[2:3]
	v_lshl_add_u64 v[40:41], s[26:27], 0, v[48:49]
	s_add_u32 s26, s28, 0x2d30000
	v_lshl_add_u64 v[20:21], v[20:21], 0, v[0:1]
	v_lshl_add_u64 v[44:45], v[40:41], 0, v[0:1]
	s_addc_u32 s27, s29, 0
	s_nop 0
	s_nop 0
	s_nop 0
	v_lshl_add_u64 v[20:21], s[26:27], 0, v[2:3]
	v_lshl_add_u64 v[48:49], s[26:27], 0, v[48:49]
	v_lshl_add_u64 v[20:21], v[20:21], 0, v[0:1]
	v_lshl_add_u64 v[52:53], v[48:49], 0, v[0:1]
	s_nop 0
	s_nop 0
	s_nop 0
	v_and_b32_e32 v1, 31, v68
	v_bfe_u32 v87, v68, 5, 1
	s_waitcnt vmcnt(0)
	v_cvt_pk_f16_f32 v11, v10, v11
	v_cvt_pk_f16_f32 v10, v8, v9
	v_cvt_pk_f16_f32 v8, v4, v5
	v_mul_u32_u24_e32 v2, 0x90, v23
	v_lshlrev_b32_e32 v4, 1, v22
	v_lshrrev_b32_sdwa v5, v204, v68 dst_sel:DWORD dst_unused:UNUSED_PAD src0_sel:DWORD src1_sel:BYTE_0
	v_cvt_pk_f16_f32 v19, v18, v19
	v_cvt_pk_f16_f32 v18, v16, v17
	v_cvt_pk_f16_f32 v16, v12, v13
	v_add3_u32 v2, s35, v2, v4
	v_mul_u32_u24_e32 v4, 0x90, v56
	v_and_or_b32 v109, v5, 32, v1
	v_lshlrev_b32_e32 v13, 4, v87
	v_mul_u32_u24_e32 v1, 0x90, v1
	v_cvt_pk_f16_f32 v17, v14, v15
	v_add3_u32 v0, s35, v4, v0
	v_add3_u32 v1, s35, v1, v13
	v_cvt_pk_f16_f32 v9, v6, v7
	ds_write_b128 v2, v[16:19]
	ds_write_b128 v2, v[8:11] offset:16
	v_lshrrev_b32_sdwa v108, v219, v68 dst_sel:DWORD dst_unused:UNUSED_PAD src0_sel:DWORD src1_sel:BYTE_0
	v_mov_b32_e32 v12, s35
	s_movk_i32 s26, 0x4800
	v_mul_u32_u24_e32 v2, 0x90, v109
	ds_write_b128 v0, v[184:187] offset:9216
	ds_write_b128 v0, v[188:191] offset:13824
	ds_write_b128 v0, v[192:195] offset:18432
	ds_write_b128 v0, v[196:199] offset:23040
	ds_write_b128 v0, v[238:241] offset:27648
	ds_write_b128 v0, v[242:245] offset:32256
	ds_write_b128 v0, v[246:249] offset:36864
	ds_write_b128 v0, v[250:253] offset:41472
	s_waitcnt lgkmcnt(0)
	s_barrier
	ds_read_b128 v[4:7], v1
	v_mad_u32_u24 v0, v108, s26, v12
	v_add3_u32 v0, v0, v2, v13
	ds_read_b128 v[36:39], v0 offset:9216
	ds_read_b128 v[40:43], v1 offset:32
	ds_read_b128 v[70:73], v0 offset:9248
	ds_read_b128 v[52:55], v0 offset:18432
	ds_read_b128 v[74:77], v0 offset:18464
	s_waitcnt lgkmcnt(4)
	v_mfma_f32_32x32x16_f16 v[20:35], v[4:7], v[36:39], 0
	v_mul_u32_u24_e32 v2, 0x240, v87
	v_lshlrev_b32_e32 v48, 1, v109
	v_add3_u32 v49, s35, v48, v2
	v_add3_u32 v2, s35, v2, v48
	ds_read_b128 v[78:81], v0 offset:9280
	s_waitcnt lgkmcnt(2)
	v_mfma_f32_32x32x16_f16 v[4:19], v[4:7], v[52:55], 0
	v_mfma_f32_32x32x16_f16 v[20:35], v[40:43], v[70:73], v[20:35]
	s_waitcnt lgkmcnt(1)
	v_mfma_f32_32x32x16_f16 v[4:19], v[40:43], v[74:77], v[4:19]
	ds_read_b128 v[40:43], v1 offset:64
	ds_read_b128 v[44:47], v1 offset:96
	ds_read_b128 v[88:91], v0 offset:9312
	ds_read_b128 v[92:95], v0 offset:18496
	ds_read_b128 v[56:59], v1 offset:4608
	ds_read_b128 v[82:85], v1 offset:4640
	ds_read_b128 v[96:99], v1 offset:4672
	ds_read_b128 v[100:103], v1 offset:4704
	ds_read_b128 v[104:107], v0 offset:18528
	ds_read_u16 v69, v49
	ds_read_u16 v86, v49 offset:144
	ds_read_u16 v110, v49 offset:288
	ds_read_u16 v111, v49 offset:432
	ds_read_u16 v112, v49 offset:1152
	ds_read_u16 v113, v49 offset:1296
	ds_read_u16 v114, v49 offset:1440
	ds_read_u16 v115, v49 offset:1584
	ds_read_u16 v116, v2 offset:4608
	ds_read_u16 v117, v2 offset:4752
	ds_read_u16 v118, v2 offset:4896
	ds_read_u16 v119, v2 offset:5040
	ds_read_u16 v120, v2 offset:5760
	ds_read_u16 v121, v2 offset:5904
	ds_read_u16 v122, v2 offset:6048
	ds_read_u16 v123, v2 offset:6192
	ds_read_u16 v124, v49 offset:2304
	ds_read_u16 v125, v49 offset:2448
	ds_read_u16 v126, v49 offset:2592
	ds_read_u16 v127, v49 offset:2736
	ds_read_u16 v128, v49 offset:3456
	ds_read_u16 v129, v49 offset:3600
	ds_read_u16 v130, v49 offset:3744
	ds_read_u16 v131, v49 offset:3888
	ds_read_u16 v132, v2 offset:6912
	ds_read_u16 v133, v2 offset:7056
	ds_read_u16 v134, v2 offset:7200
	ds_read_u16 v135, v2 offset:7344
	ds_read_u16 v136, v2 offset:8064
	ds_read_u16 v137, v2 offset:8208
	ds_read_u16 v138, v2 offset:8352
	ds_read_u16 v2, v2 offset:8496
	s_waitcnt lgkmcnt(0)
	s_barrier
	s_load_dwordx4 s[28:31], s[22:23], 0xc0
	s_load_dwordx2 s[26:27], s[22:23], 0xb0
	v_lshlrev_b32_e32 v0, 9, v108
	v_or3_b32 v0, v109, v0, s37
	v_lshlrev_b32_e32 v0, 2, v0
	s_waitcnt lgkmcnt(0)
	global_load_dword v139, v0, s[30:31]
	v_mfma_f32_32x32x16_f16 v[20:35], v[40:43], v[78:81], v[20:35]
	global_load_dword v1, v0, s[26:27]
	s_nop 0
	global_load_dword v0, v0, s[28:29]
	v_cvt_f32_f16_e32 v140, v69
	s_mov_b32 s26, 0x3f2aaaab
	v_cvt_f32_f16_e32 v141, v86
	v_cvt_f32_f16_e32 v116, v116
	v_cvt_f32_f16_e32 v117, v117
	v_cvt_f32_f16_e32 v110, v110
	v_mfma_f32_32x32x16_f16 v[4:19], v[40:43], v[92:95], v[4:19]
	v_cvt_f32_f16_e32 v111, v111
	v_cvt_f32_f16_e32 v118, v118
	v_cvt_f32_f16_e32 v119, v119
	v_cvt_f32_f16_e32 v112, v112
	v_cvt_f32_f16_e32 v113, v113
	v_cvt_f32_f16_e32 v120, v120
	v_cvt_f32_f16_e32 v121, v121
	v_mfma_f32_32x32x16_f16 v[20:35], v[44:47], v[88:91], v[20:35]
	v_cvt_f32_f16_e32 v114, v114
	v_cvt_f32_f16_e32 v86, v122
	v_cvt_f32_f16_e32 v2, v2
	s_waitcnt vmcnt(2)
	v_mul_f32_e32 v69, 0xbfb8aa3b, v139
	v_mfma_f32_32x32x16_f16 v[4:19], v[44:47], v[104:107], v[4:19]
	s_waitcnt vmcnt(1)
	s_nop 4
	v_add_f32_e32 v20, v20, v1
	v_mul_f32_e32 v20, 0xbfb8aa3b, v20
	v_add_f32_e32 v21, v21, v1
	v_mul_f32_e32 v21, 0xbfb8aa3b, v21
	v_exp_f32_e32 v21, v21
	v_add_f32_e32 v22, v22, v1
	v_mul_f32_e32 v22, 0xbfb8aa3b, v22
	v_mfma_f32_32x32x16_f16 v[36:51], v[56:59], v[36:39], 0
	s_waitcnt vmcnt(0)
	v_add_f32_e32 v4, v4, v0
	v_mul_f32_e32 v4, 0xbfb8aa3b, v4
	v_exp_f32_e32 v4, v4
	v_add_f32_e32 v21, 1.0, v21
	v_rcp_f32_e32 v21, v21
	v_add_f32_e32 v5, v5, v0
	v_add_f32_e32 v4, 1.0, v4
	v_mfma_f32_32x32x16_f16 v[36:51], v[82:85], v[70:73], v[36:51]
	v_mul_f32_e32 v21, 0xc1000000, v21
	v_mul_f32_e32 v5, 0xbfb8aa3b, v5
	v_exp_f32_e32 v5, v5
	v_exp_f32_e32 v22, v22
	v_add_f32_e32 v6, v6, v0
	v_add_f32_e32 v23, v23, v1
	v_add_f32_e32 v5, 1.0, v5
	v_mfma_f32_32x32x16_f16 v[52:67], v[56:59], v[52:55], 0
	v_rcp_f32_e32 v5, v5
	v_mul_f32_e32 v6, 0xbfb8aa3b, v6
	v_mul_f32_e32 v23, 0xbfb8aa3b, v23
	v_exp_f32_e32 v6, v6
	v_exp_f32_e32 v23, v23
	v_add_f32_e32 v7, v7, v0
	v_mul_f32_e32 v7, 0xbfb8aa3b, v7
	v_mfma_f32_32x32x16_f16 v[36:51], v[96:99], v[78:81], v[36:51]
	v_add_f32_e32 v23, 1.0, v23
	v_rcp_f32_e32 v23, v23
	v_exp_f32_e32 v7, v7
	v_add_f32_e32 v9, v9, v0
	v_mul_f32_e32 v9, 0xbfb8aa3b, v9
	v_mul_f32_e32 v23, 0xc1000000, v23
	v_add_f32_e32 v7, 1.0, v7
	v_mfma_f32_32x32x16_f16 v[52:67], v[82:85], v[74:77], v[52:67]
	v_rcp_f32_e32 v7, v7
	v_exp_f32_e32 v9, v9
	v_add_f32_e32 v11, v11, v0
	v_mul_f32_e32 v11, 0xbfb8aa3b, v11
	v_exp_f32_e32 v11, v11
	v_add_f32_e32 v9, 1.0, v9
	v_rcp_f32_e32 v9, v9
	v_mfma_f32_32x32x16_f16 v[36:51], v[100:103], v[88:91], v[36:51]
	v_exp_f32_e32 v90, v69
	v_cvt_f32_f16_e32 v85, v115
	v_cvt_f32_f16_e32 v84, v123
	v_cvt_f32_f16_e32 v83, v124
	v_add_f32_e32 v91, 1.0, v90
	v_add_f32_e32 v88, -1.0, v91
	v_sub_f32_e32 v89, v88, v91
	v_add_f32_e32 v89, 1.0, v89
	v_sub_f32_e32 v88, v90, v88
	v_mfma_f32_32x32x16_f16 v[52:67], v[96:99], v[92:95], v[52:67]
	v_add_f32_e32 v92, v88, v89
	v_frexp_mant_f32_e32 v93, v91
	v_cvt_f64_f32_e32 v[88:89], v91
	v_frexp_exp_i32_f64_e32 v88, v[88:89]
	v_cmp_gt_f32_e32 vcc, s26, v93
	s_mov_b32 s26, 0x3f317218
	v_add_f32_e32 v36, v36, v1
	v_subbrev_co_u32_e32 v88, vcc, 0, v88, vcc
	v_sub_u32_e32 v89, 0, v88
	v_ldexp_f32 v91, v91, v89
	v_ldexp_f32 v89, v92, v89
	v_add_f32_e32 v92, -1.0, v91
	v_add_f32_e32 v95, 1.0, v91
	v_add_f32_e32 v93, 1.0, v92
	v_add_f32_e32 v96, -1.0, v95
	v_sub_f32_e32 v93, v91, v93
	v_sub_f32_e32 v91, v91, v96
	v_add_f32_e32 v93, v89, v93
	v_add_f32_e32 v89, v89, v91
	v_add_f32_e32 v91, v95, v89
	v_rcp_f32_e32 v96, v91
	v_add_f32_e32 v94, v92, v93
	v_sub_f32_e32 v92, v94, v92
	v_sub_f32_e32 v92, v93, v92
	v_sub_f32_e32 v93, v91, v95
	v_sub_f32_e32 v89, v89, v93
	v_mul_f32_e32 v93, v94, v96
	v_mul_f32_e32 v95, v91, v93
	v_fma_f32 v97, v93, v91, -v95
	v_fmac_f32_e32 v97, v93, v89
	v_add_f32_e32 v98, v95, v97
	v_sub_f32_e32 v99, v94, v98
	v_sub_f32_e32 v94, v94, v99
	v_sub_f32_e32 v95, v98, v95
	v_sub_f32_e32 v94, v94, v98
	v_add_f32_e32 v92, v92, v94
	v_sub_f32_e32 v94, v95, v97
	v_add_f32_e32 v92, v94, v92
	v_add_f32_e32 v94, v99, v92
	v_mul_f32_e32 v95, v96, v94
	v_mul_f32_e32 v97, v91, v95
	v_fma_f32 v91, v95, v91, -v97
	v_fmac_f32_e32 v91, v95, v89
	v_sub_f32_e32 v89, v99, v94
	v_add_f32_e32 v89, v92, v89
	v_add_f32_e32 v92, v97, v91
	v_sub_f32_e32 v98, v94, v92
	v_sub_f32_e32 v94, v94, v98
	v_sub_f32_e32 v97, v92, v97
	v_sub_f32_e32 v92, v94, v92
	v_add_f32_e32 v89, v89, v92
	v_sub_f32_e32 v91, v97, v91
	v_cvt_f32_i32_e32 v88, v88
	v_add_f32_e32 v89, v91, v89
	v_add_f32_e32 v91, v93, v95
	v_add_f32_e32 v89, v98, v89
	v_sub_f32_e32 v92, v91, v93
	v_mul_f32_e32 v89, v96, v89
	v_sub_f32_e32 v92, v95, v92
	v_add_f32_e32 v89, v92, v89
	v_mul_f32_e32 v95, 0x3f317218, v88
	v_add_f32_e32 v92, v91, v89
	v_fma_f32 v96, v88, s26, -v95
	v_mul_f32_e32 v93, v92, v92
	v_fmac_f32_e32 v96, 0xb102e308, v88
	v_sub_f32_e32 v88, v92, v91
	v_fmamk_f32 v94, v93, 0x3e9b6dac, v201
	v_sub_f32_e32 v88, v89, v88
	v_add_f32_e32 v89, v95, v96
	v_fmaak_f32 v94, v93, v94, 0x3f2aaada
	v_sub_f32_e32 v91, v89, v95
	v_ldexp_f32 v95, v92, 1
	v_mul_f32_e32 v92, v92, v93
	v_mul_f32_e32 v92, v92, v94
	v_add_f32_e32 v93, v95, v92
	v_sub_f32_e32 v94, v93, v95
	v_ldexp_f32 v88, v88, 1
	v_sub_f32_e32 v92, v92, v94
	v_add_f32_e32 v88, v88, v92
	v_add_f32_e32 v92, v93, v88
	v_sub_f32_e32 v93, v92, v93
	v_sub_f32_e32 v88, v88, v93
	v_add_f32_e32 v93, v89, v92
	v_sub_f32_e32 v94, v93, v89
	v_sub_f32_e32 v95, v93, v94
	v_sub_f32_e32 v91, v96, v91
	v_sub_f32_e32 v89, v89, v95
	v_sub_f32_e32 v92, v92, v94
	v_add_f32_e32 v89, v92, v89
	v_add_f32_e32 v92, v91, v88
	v_sub_f32_e32 v94, v92, v91
	v_sub_f32_e32 v95, v92, v94
	v_sub_f32_e32 v91, v91, v95
	v_sub_f32_e32 v88, v88, v94
	v_add_f32_e32 v89, v92, v89
	v_add_f32_e32 v88, v88, v91
	v_add_f32_e32 v91, v93, v89
	v_sub_f32_e32 v92, v91, v93
	v_sub_f32_e32 v89, v89, v92
	v_add_f32_e32 v88, v88, v89
	v_exp_f32_e32 v89, v20
	v_add_f32_e32 v88, v91, v88
	v_cmp_neq_f32_e32 vcc, s40, v90
	v_mul_f32_e32 v36, 0xbfb8aa3b, v36
	v_exp_f32_e32 v36, v36
	v_cndmask_b32_e32 v88, v215, v88, vcc
	v_cmp_ngt_f32_e32 vcc, -1.0, v90
	v_mfma_f32_32x32x16_f16 v[52:67], v[100:103], v[104:107], v[52:67]
	s_mov_b32 s26, 0x33800000
	v_cndmask_b32_e32 v88, v216, v88, vcc
	v_cmp_neq_f32_e32 vcc, -1.0, v90
	v_add_f32_e32 v36, 1.0, v36
	v_rcp_f32_e32 v36, v36
	v_cndmask_b32_e32 v20, v217, v88, vcc
	v_add_f32_e32 v88, 1.0, v89
	v_rcp_f32_e32 v88, v88
	v_cmp_lt_f32_e64 vcc, |v90|, s26
	v_mul_f32_e32 v36, 0xc1000000, v36
	s_nop 1
	v_add_f32_e32 v52, v52, v0
	v_cndmask_b32_e32 v20, v20, v90, vcc
	v_mul_f32_e32 v88, 0xc1000000, v88
	v_mul_f32_e32 v88, v88, v20
	v_mul_f32_e32 v88, 0x3fb8aa3b, v88
	v_exp_f32_e32 v88, v88
	v_mul_f32_e32 v36, v36, v20
	v_mul_f32_e32 v36, 0x3fb8aa3b, v36
	v_rcp_f32_e32 v90, v4
	v_fma_f32 v4, -v88, v88, 1.0
	v_mul_f32_e32 v52, 0xbfb8aa3b, v52
	v_exp_f32_e32 v36, v36
	v_max_f32_e32 v4, 0, v4
	v_exp_f32_e32 v52, v52
	v_sqrt_f32_e32 v91, v4
	v_lshlrev_b32_e32 v4, 2, v109
	v_lshlrev_b32_e32 v89, 14, v108
	v_lshl_or_b32 v4, v87, 10, v4
	v_add3_u32 v4, s35, v89, v4
	v_fma_f32 v89, -v36, v36, 1.0
	v_mul_f32_e32 v21, v21, v20
	v_add_f32_e32 v37, v37, v1
	v_add_f32_e32 v52, 1.0, v52
	v_max_f32_e32 v89, 0, v89
	v_mul_f32_e32 v21, 0x3fb8aa3b, v21
	v_mul_f32_e32 v37, 0xbfb8aa3b, v37
	v_rcp_f32_e32 v52, v52
	v_sqrt_f32_e32 v89, v89
	v_exp_f32_e32 v21, v21
	v_exp_f32_e32 v37, v37
	v_mul_f32_e32 v87, v90, v91
	v_mul_f32_e32 v52, v52, v89
	v_fma_f32 v89, -v21, v21, 1.0
	ds_write2st64_b32 v4, v88, v21 offset1:1
	v_add_f32_e32 v21, 1.0, v37
	v_rcp_f32_e32 v21, v21
	v_add_f32_e32 v37, v53, v0
	v_max_f32_e32 v89, 0, v89
	v_mul_f32_e32 v37, 0xbfb8aa3b, v37
	v_mul_f32_e32 v21, 0xc1000000, v21
	v_mul_f32_e32 v21, v21, v20
	v_mul_f32_e32 v21, 0x3fb8aa3b, v21
	v_exp_f32_e32 v21, v21
	v_sqrt_f32_e32 v89, v89
	v_exp_f32_e32 v37, v37
	v_mul_f32_e32 v87, v87, v140
	v_fma_f32 v53, -v21, v21, 1.0
	v_mul_f32_e32 v5, v5, v89
	v_add_f32_e32 v37, 1.0, v37
	v_max_f32_e32 v53, 0, v53
	v_mul_f32_e32 v5, v5, v141
	v_rcp_f32_e32 v37, v37
	v_sqrt_f32_e32 v53, v53
	ds_write2st64_b32 v4, v87, v5 offset0:128 offset1:129
	ds_write2st64_b32 v4, v36, v21 offset0:32 offset1:33
	v_add_f32_e32 v21, 1.0, v22
	v_rcp_f32_e32 v21, v21
	v_mul_f32_e32 v5, v37, v53
	v_mul_f32_e32 v52, v52, v116
	v_mul_f32_e32 v5, v5, v117
	ds_write2st64_b32 v4, v52, v5 offset0:160 offset1:161
	v_add_f32_e32 v5, 1.0, v6
	v_mul_f32_e32 v6, 0xc1000000, v21
	v_add_f32_e32 v21, v38, v1
	v_mul_f32_e32 v21, 0xbfb8aa3b, v21
	v_exp_f32_e32 v21, v21
	v_mul_f32_e32 v6, v6, v20
	v_mul_f32_e32 v23, v23, v20
	v_mul_f32_e32 v6, 0x3fb8aa3b, v6
	v_add_f32_e32 v21, 1.0, v21
	v_rcp_f32_e32 v21, v21
	v_mul_f32_e32 v23, 0x3fb8aa3b, v23
	v_exp_f32_e32 v6, v6
	v_exp_f32_e32 v23, v23
	v_mul_f32_e32 v21, 0xc1000000, v21
	v_mul_f32_e32 v21, v21, v20
	v_fma_f32 v22, -v6, v6, 1.0
	ds_write2st64_b32 v4, v6, v23 offset0:2 offset1:3
	v_add_f32_e32 v6, v39, v1
	v_add_f32_e32 v36, v54, v0
	v_mul_f32_e32 v21, 0x3fb8aa3b, v21
	v_mul_f32_e32 v6, 0xbfb8aa3b, v6
	v_mul_f32_e32 v36, 0xbfb8aa3b, v36
	v_exp_f32_e32 v21, v21
	v_exp_f32_e32 v6, v6
	v_exp_f32_e32 v36, v36
	v_max_f32_e32 v22, 0, v22
	v_fma_f32 v37, -v21, v21, 1.0
	v_add_f32_e32 v6, 1.0, v6
	v_add_f32_e32 v36, 1.0, v36
	v_max_f32_e32 v37, 0, v37
	v_rcp_f32_e32 v6, v6
	v_rcp_f32_e32 v5, v5
	v_sqrt_f32_e32 v22, v22
	v_rcp_f32_e32 v36, v36
	v_sqrt_f32_e32 v37, v37
	v_fma_f32 v23, -v23, v23, 1.0
	v_max_f32_e32 v23, 0, v23
	v_mul_f32_e32 v6, 0xc1000000, v6
	v_mul_f32_e32 v5, v5, v22
	v_mul_f32_e32 v22, v36, v37
	v_sqrt_f32_e32 v23, v23
	v_add_f32_e32 v36, v55, v0
	v_mul_f32_e32 v6, v6, v20
	v_mul_f32_e32 v36, 0xbfb8aa3b, v36
	v_mul_f32_e32 v6, 0x3fb8aa3b, v6
	v_exp_f32_e32 v36, v36
	v_exp_f32_e32 v6, v6
	v_mul_f32_e32 v7, v7, v23
	v_mul_f32_e32 v5, v5, v110
	v_mul_f32_e32 v7, v7, v111
	v_add_f32_e32 v23, 1.0, v36
	v_fma_f32 v36, -v6, v6, 1.0
	ds_write2st64_b32 v4, v5, v7 offset0:130 offset1:131
	ds_write2st64_b32 v4, v21, v6 offset0:34 offset1:35
	v_add_f32_e32 v6, v24, v1
	v_mul_f32_e32 v6, 0xbfb8aa3b, v6
	v_exp_f32_e32 v6, v6
	v_max_f32_e32 v36, 0, v36
	v_rcp_f32_e32 v23, v23
	v_sqrt_f32_e32 v36, v36
	v_add_f32_e32 v6, 1.0, v6
	v_rcp_f32_e32 v6, v6
	v_add_f32_e32 v7, v8, v0
	v_mul_f32_e32 v7, 0xbfb8aa3b, v7
	v_exp_f32_e32 v7, v7
	v_mul_f32_e32 v6, 0xc1000000, v6
	v_mul_f32_e32 v6, v6, v20
	v_mul_f32_e32 v6, 0x3fb8aa3b, v6
	v_exp_f32_e32 v6, v6
	v_mul_f32_e32 v5, v23, v36
	v_mul_f32_e32 v22, v22, v118
	v_mul_f32_e32 v5, v5, v119
	v_fma_f32 v8, -v6, v6, 1.0
	v_add_f32_e32 v21, v56, v0
	ds_write2st64_b32 v4, v22, v5 offset0:162 offset1:163
	v_add_f32_e32 v5, 1.0, v7
	v_max_f32_e32 v8, 0, v8
	v_mul_f32_e32 v21, 0xbfb8aa3b, v21
	v_rcp_f32_e32 v5, v5
	v_sqrt_f32_e32 v8, v8
	v_exp_f32_e32 v21, v21
	v_add_f32_e32 v7, v40, v1
	v_mul_f32_e32 v7, 0xbfb8aa3b, v7
	v_mul_f32_e32 v5, v5, v8
	v_add_f32_e32 v8, 1.0, v21
	v_add_f32_e32 v21, v25, v1
	v_mul_f32_e32 v21, 0xbfb8aa3b, v21
	v_exp_f32_e32 v21, v21
	v_exp_f32_e32 v7, v7
	v_mul_f32_e32 v5, v5, v112
	v_rcp_f32_e32 v8, v8
	v_add_f32_e32 v21, 1.0, v21
	v_rcp_f32_e32 v21, v21
	v_add_f32_e32 v7, 1.0, v7
	v_rcp_f32_e32 v7, v7
	v_cvt_f32_f16_e32 v81, v125
	v_mul_f32_e32 v21, 0xc1000000, v21
	v_mul_f32_e32 v21, v21, v20
	v_mul_f32_e32 v21, 0x3fb8aa3b, v21
	v_exp_f32_e32 v21, v21
	v_mul_f32_e32 v7, 0xc1000000, v7
	v_mul_f32_e32 v7, v7, v20
	v_mul_f32_e32 v7, 0x3fb8aa3b, v7
	v_fma_f32 v23, -v21, v21, 1.0
	v_max_f32_e32 v23, 0, v23
	v_sqrt_f32_e32 v23, v23
	ds_write2st64_b32 v4, v6, v21 offset0:8 offset1:9
	v_exp_f32_e32 v7, v7
	v_add_f32_e32 v21, v57, v0
	v_mul_f32_e32 v6, v9, v23
	v_add_f32_e32 v9, v41, v1
	v_mul_f32_e32 v9, 0xbfb8aa3b, v9
	v_exp_f32_e32 v9, v9
	v_mul_f32_e32 v6, v6, v113
	ds_write2st64_b32 v4, v5, v6 offset0:136 offset1:137
	v_fma_f32 v22, -v7, v7, 1.0
	v_add_f32_e32 v9, 1.0, v9
	v_rcp_f32_e32 v9, v9
	v_mul_f32_e32 v21, 0xbfb8aa3b, v21
	v_exp_f32_e32 v21, v21
	v_max_f32_e32 v22, 0, v22
	v_mul_f32_e32 v6, 0xc1000000, v9
	v_mul_f32_e32 v6, v6, v20
	v_add_f32_e32 v9, v26, v1
	v_mul_f32_e32 v6, 0x3fb8aa3b, v6
	v_mul_f32_e32 v9, 0xbfb8aa3b, v9
	v_exp_f32_e32 v6, v6
	v_exp_f32_e32 v9, v9
	v_add_f32_e32 v5, 1.0, v21
	v_rcp_f32_e32 v5, v5
	ds_write2st64_b32 v4, v7, v6 offset0:40 offset1:41
	v_add_f32_e32 v7, 1.0, v9
	v_rcp_f32_e32 v7, v7
	v_fma_f32 v6, -v6, v6, 1.0
	v_max_f32_e32 v6, 0, v6
	v_add_f32_e32 v9, v10, v0
	v_mul_f32_e32 v7, 0xc1000000, v7
	v_mul_f32_e32 v7, v7, v20
	v_mul_f32_e32 v7, 0x3fb8aa3b, v7
	v_mul_f32_e32 v9, 0xbfb8aa3b, v9
	v_exp_f32_e32 v7, v7
	v_sqrt_f32_e32 v6, v6
	v_exp_f32_e32 v9, v9
	v_sqrt_f32_e32 v22, v22
	v_fma_f32 v10, -v7, v7, 1.0
	v_mul_f32_e32 v5, v5, v6
	v_add_f32_e32 v6, v42, v1
	v_add_f32_e32 v9, 1.0, v9
	v_max_f32_e32 v10, 0, v10
	v_mul_f32_e32 v6, 0xbfb8aa3b, v6
	v_rcp_f32_e32 v9, v9
	v_sqrt_f32_e32 v10, v10
	v_exp_f32_e32 v6, v6
	v_mul_f32_e32 v8, v8, v22
	v_mul_f32_e32 v8, v8, v120
	v_mul_f32_e32 v5, v5, v121
	ds_write2st64_b32 v4, v8, v5 offset0:168 offset1:169
	v_mul_f32_e32 v5, v9, v10
	v_add_f32_e32 v6, 1.0, v6
	v_add_f32_e32 v9, v27, v1
	v_rcp_f32_e32 v6, v6
	v_mul_f32_e32 v9, 0xbfb8aa3b, v9
	v_exp_f32_e32 v9, v9
	v_add_f32_e32 v8, v58, v0
	v_mul_f32_e32 v6, 0xc1000000, v6
	v_mul_f32_e32 v6, v6, v20
	v_add_f32_e32 v9, 1.0, v9
	v_mul_f32_e32 v6, 0x3fb8aa3b, v6
	v_rcp_f32_e32 v9, v9
	v_mul_f32_e32 v8, 0xbfb8aa3b, v8
	v_exp_f32_e32 v6, v6
	v_exp_f32_e32 v8, v8
	v_mul_f32_e32 v9, 0xc1000000, v9
	v_mul_f32_e32 v9, v9, v20
	v_fma_f32 v10, -v6, v6, 1.0
	v_add_f32_e32 v21, v43, v1
	v_add_f32_e32 v8, 1.0, v8
	v_max_f32_e32 v10, 0, v10
	v_mul_f32_e32 v9, 0x3fb8aa3b, v9
	v_mul_f32_e32 v21, 0xbfb8aa3b, v21
	v_rcp_f32_e32 v8, v8
	v_sqrt_f32_e32 v10, v10
	v_exp_f32_e32 v9, v9
	v_exp_f32_e32 v21, v21
	v_mul_f32_e32 v5, v5, v114
	v_mul_f32_e32 v8, v8, v10
	v_add_f32_e32 v10, 1.0, v11
	v_fma_f32 v11, -v9, v9, 1.0
	ds_write2st64_b32 v4, v7, v9 offset0:10 offset1:11
	v_add_f32_e32 v9, 1.0, v21
	v_rcp_f32_e32 v9, v9
	v_max_f32_e32 v11, 0, v11
	v_rcp_f32_e32 v10, v10
	v_sqrt_f32_e32 v11, v11
	v_mul_f32_e32 v9, 0xc1000000, v9
	v_mul_f32_e32 v9, v9, v20
	v_mul_f32_e32 v9, 0x3fb8aa3b, v9
	v_mul_f32_e32 v7, v10, v11
	v_add_f32_e32 v10, v59, v0
	v_mul_f32_e32 v10, 0xbfb8aa3b, v10
	v_exp_f32_e32 v9, v9
	v_exp_f32_e32 v10, v10
	v_mul_f32_e32 v7, v7, v85
	ds_write2st64_b32 v4, v5, v7 offset0:138 offset1:139
	ds_write2st64_b32 v4, v6, v9 offset0:42 offset1:43
	v_fma_f32 v11, -v9, v9, 1.0
	v_add_f32_e32 v10, 1.0, v10
	v_max_f32_e32 v11, 0, v11
	v_rcp_f32_e32 v10, v10
	v_sqrt_f32_e32 v11, v11
	v_add_f32_e32 v7, v12, v0
	v_mul_f32_e32 v7, 0xbfb8aa3b, v7
	v_exp_f32_e32 v7, v7
	v_mul_f32_e32 v5, v10, v11
	v_mul_f32_e32 v8, v8, v86
	v_mul_f32_e32 v5, v5, v84
	v_add_f32_e32 v21, v28, v1
	ds_write2st64_b32 v4, v8, v5 offset0:170 offset1:171
	v_add_f32_e32 v5, 1.0, v7
	v_add_f32_e32 v7, v44, v1
	v_mul_f32_e32 v21, 0xbfb8aa3b, v21
	v_mul_f32_e32 v7, 0xbfb8aa3b, v7
	v_exp_f32_e32 v21, v21
	v_exp_f32_e32 v7, v7
	v_add_f32_e32 v9, v60, v0
	v_mul_f32_e32 v9, 0xbfb8aa3b, v9
	v_add_f32_e32 v6, 1.0, v21
	v_add_f32_e32 v7, 1.0, v7
	v_rcp_f32_e32 v6, v6
	v_rcp_f32_e32 v7, v7
	v_exp_f32_e32 v9, v9
	v_add_f32_e32 v11, v29, v1
	v_mul_f32_e32 v6, 0xc1000000, v6
	v_mul_f32_e32 v7, 0xc1000000, v7
	v_mul_f32_e32 v6, v6, v20
	v_mul_f32_e32 v7, v7, v20
	v_mul_f32_e32 v6, 0x3fb8aa3b, v6
	v_mul_f32_e32 v7, 0x3fb8aa3b, v7
	v_exp_f32_e32 v6, v6
	v_exp_f32_e32 v7, v7
	v_add_f32_e32 v9, 1.0, v9
	v_mul_f32_e32 v11, 0xbfb8aa3b, v11
	v_fma_f32 v8, -v6, v6, 1.0
	v_fma_f32 v10, -v7, v7, 1.0
	v_max_f32_e32 v8, 0, v8
	v_max_f32_e32 v10, 0, v10
	v_rcp_f32_e32 v5, v5
	v_sqrt_f32_e32 v8, v8
	v_rcp_f32_e32 v9, v9
	v_sqrt_f32_e32 v10, v10
	v_exp_f32_e32 v11, v11
	v_mul_f32_e32 v5, v5, v8
	v_mul_f32_e32 v5, v5, v83
	v_mul_f32_e32 v8, v9, v10
	v_add_f32_e32 v9, 1.0, v11
	v_rcp_f32_e32 v9, v9
	v_add_f32_e32 v10, v13, v0
	v_mul_f32_e32 v10, 0xbfb8aa3b, v10
	v_exp_f32_e32 v10, v10
	v_mul_f32_e32 v9, 0xc1000000, v9
	v_mul_f32_e32 v9, v9, v20
	v_mul_f32_e32 v9, 0x3fb8aa3b, v9
	v_exp_f32_e32 v9, v9
	v_add_f32_e32 v10, 1.0, v10
	v_rcp_f32_e32 v10, v10
	v_add_f32_e32 v11, v61, v0
	ds_write2st64_b32 v4, v6, v9 offset0:16 offset1:17
	v_add_f32_e32 v6, v45, v1
	v_mul_f32_e32 v6, 0xbfb8aa3b, v6
	v_exp_f32_e32 v6, v6
	v_fma_f32 v9, -v9, v9, 1.0
	v_max_f32_e32 v9, 0, v9
	v_sqrt_f32_e32 v9, v9
	v_add_f32_e32 v6, 1.0, v6
	v_rcp_f32_e32 v6, v6
	v_mul_f32_e32 v11, 0xbfb8aa3b, v11
	v_exp_f32_e32 v11, v11
	v_mul_f32_e32 v9, v10, v9
	v_mul_f32_e32 v6, 0xc1000000, v6
	v_mul_f32_e32 v6, v6, v20
	v_mul_f32_e32 v6, 0x3fb8aa3b, v6
	v_exp_f32_e32 v6, v6
	v_mul_f32_e32 v9, v9, v81
	v_add_f32_e32 v10, 1.0, v11
	ds_write2st64_b32 v4, v5, v9 offset0:144 offset1:145
	ds_write2st64_b32 v4, v7, v6 offset0:48 offset1:49
	v_fma_f32 v11, -v6, v6, 1.0
	v_add_f32_e32 v6, v30, v1
	v_mul_f32_e32 v6, 0xbfb8aa3b, v6
	v_exp_f32_e32 v6, v6
	v_max_f32_e32 v11, 0, v11
	v_rcp_f32_e32 v10, v10
	v_sqrt_f32_e32 v11, v11
	v_add_f32_e32 v6, 1.0, v6
	v_rcp_f32_e32 v6, v6
	v_cvt_f32_f16_e32 v82, v132
	v_cvt_f32_f16_e32 v80, v133
	v_add_f32_e32 v7, v14, v0
	v_mul_f32_e32 v6, 0xc1000000, v6
	v_mul_f32_e32 v6, v6, v20
	v_mul_f32_e32 v6, 0x3fb8aa3b, v6
	v_mul_f32_e32 v7, 0xbfb8aa3b, v7
	v_exp_f32_e32 v6, v6
	v_exp_f32_e32 v7, v7
	v_mul_f32_e32 v5, v10, v11
	v_mul_f32_e32 v8, v8, v82
	v_mul_f32_e32 v5, v5, v80
	ds_write2st64_b32 v4, v8, v5 offset0:176 offset1:177
	v_fma_f32 v8, -v6, v6, 1.0
	v_add_f32_e32 v9, v62, v0
	v_add_f32_e32 v5, 1.0, v7
	v_max_f32_e32 v8, 0, v8
	v_mul_f32_e32 v9, 0xbfb8aa3b, v9
	v_rcp_f32_e32 v5, v5
	v_sqrt_f32_e32 v8, v8
	v_exp_f32_e32 v9, v9
	v_add_f32_e32 v7, v46, v1
	v_mul_f32_e32 v7, 0xbfb8aa3b, v7
	v_mul_f32_e32 v5, v5, v8
	v_add_f32_e32 v8, 1.0, v9
	v_add_f32_e32 v9, v31, v1
	v_mul_f32_e32 v9, 0xbfb8aa3b, v9
	v_exp_f32_e32 v9, v9
	v_exp_f32_e32 v7, v7
	v_add_f32_e32 v11, v15, v0
	v_mul_f32_e32 v11, 0xbfb8aa3b, v11
	v_add_f32_e32 v9, 1.0, v9
	v_rcp_f32_e32 v9, v9
	v_exp_f32_e32 v11, v11
	v_add_f32_e32 v7, 1.0, v7
	v_rcp_f32_e32 v7, v7
	v_mul_f32_e32 v9, 0xc1000000, v9
	v_mul_f32_e32 v9, v9, v20
	v_mul_f32_e32 v9, 0x3fb8aa3b, v9
	v_exp_f32_e32 v9, v9
	v_add_f32_e32 v11, 1.0, v11
	v_rcp_f32_e32 v11, v11
	v_cvt_f32_f16_e32 v79, v126
	v_fma_f32 v12, -v9, v9, 1.0
	ds_write2st64_b32 v4, v6, v9 offset0:18 offset1:19
	v_add_f32_e32 v9, v47, v1
	v_mul_f32_e32 v9, 0xbfb8aa3b, v9
	v_exp_f32_e32 v9, v9
	v_max_f32_e32 v12, 0, v12
	v_sqrt_f32_e32 v12, v12
	v_cvt_f32_f16_e32 v77, v127
	v_mul_f32_e32 v7, 0xc1000000, v7
	v_add_f32_e32 v9, 1.0, v9
	v_mul_f32_e32 v7, v7, v20
	v_rcp_f32_e32 v9, v9
	v_mul_f32_e32 v7, 0x3fb8aa3b, v7
	v_exp_f32_e32 v7, v7
	v_mul_f32_e32 v6, v11, v12
	v_mul_f32_e32 v5, v5, v79
	v_mul_f32_e32 v6, v6, v77
	ds_write2st64_b32 v4, v5, v6 offset0:146 offset1:147
	v_mul_f32_e32 v6, 0xc1000000, v9
	v_mul_f32_e32 v6, v6, v20
	v_add_f32_e32 v9, v32, v1
	v_fma_f32 v10, -v7, v7, 1.0
	v_mul_f32_e32 v6, 0x3fb8aa3b, v6
	v_mul_f32_e32 v9, 0xbfb8aa3b, v9
	v_max_f32_e32 v10, 0, v10
	v_exp_f32_e32 v6, v6
	v_exp_f32_e32 v9, v9
	v_rcp_f32_e32 v8, v8
	v_sqrt_f32_e32 v10, v10
	ds_write2st64_b32 v4, v7, v6 offset0:50 offset1:51
	v_add_f32_e32 v7, 1.0, v9
	v_rcp_f32_e32 v7, v7
	v_mul_f32_e32 v8, v8, v10
	v_add_f32_e32 v10, v63, v0
	v_mul_f32_e32 v10, 0xbfb8aa3b, v10
	v_exp_f32_e32 v10, v10
	v_mul_f32_e32 v7, 0xc1000000, v7
	v_fma_f32 v6, -v6, v6, 1.0
	v_mul_f32_e32 v7, v7, v20
	v_add_f32_e32 v5, 1.0, v10
	v_max_f32_e32 v6, 0, v6
	v_add_f32_e32 v9, v16, v0
	v_mul_f32_e32 v7, 0x3fb8aa3b, v7
	v_rcp_f32_e32 v5, v5
	v_mul_f32_e32 v9, 0xbfb8aa3b, v9
	v_exp_f32_e32 v7, v7
	v_sqrt_f32_e32 v6, v6
	v_exp_f32_e32 v9, v9
	v_cvt_f32_f16_e32 v78, v134
	v_fma_f32 v10, -v7, v7, 1.0
	v_mul_f32_e32 v5, v5, v6
	v_add_f32_e32 v6, v48, v1
	v_cvt_f32_f16_e32 v76, v135
	v_add_f32_e32 v9, 1.0, v9
	v_max_f32_e32 v10, 0, v10
	v_mul_f32_e32 v6, 0xbfb8aa3b, v6
	v_rcp_f32_e32 v9, v9
	v_sqrt_f32_e32 v10, v10
	v_exp_f32_e32 v6, v6
	v_mul_f32_e32 v8, v8, v78
	v_mul_f32_e32 v5, v5, v76
	ds_write2st64_b32 v4, v8, v5 offset0:178 offset1:179
	v_mul_f32_e32 v5, v9, v10
	v_add_f32_e32 v6, 1.0, v6
	v_add_f32_e32 v9, v33, v1
	v_rcp_f32_e32 v6, v6
	v_mul_f32_e32 v9, 0xbfb8aa3b, v9
	v_exp_f32_e32 v9, v9
	v_add_f32_e32 v8, v64, v0
	v_mul_f32_e32 v6, 0xc1000000, v6
	v_mul_f32_e32 v6, v6, v20
	v_add_f32_e32 v9, 1.0, v9
	v_mul_f32_e32 v6, 0x3fb8aa3b, v6
	v_rcp_f32_e32 v9, v9
	v_mul_f32_e32 v8, 0xbfb8aa3b, v8
	v_exp_f32_e32 v6, v6
	v_exp_f32_e32 v8, v8
	v_mul_f32_e32 v9, 0xc1000000, v9
	v_add_f32_e32 v11, v17, v0
	v_fma_f32 v10, -v6, v6, 1.0
	v_mul_f32_e32 v9, v9, v20
	v_add_f32_e32 v12, v49, v1
	v_add_f32_e32 v8, 1.0, v8
	v_max_f32_e32 v10, 0, v10
	v_mul_f32_e32 v11, 0xbfb8aa3b, v11
	v_mul_f32_e32 v9, 0x3fb8aa3b, v9
	v_mul_f32_e32 v12, 0xbfb8aa3b, v12
	v_rcp_f32_e32 v8, v8
	v_sqrt_f32_e32 v10, v10
	v_exp_f32_e32 v11, v11
	v_exp_f32_e32 v9, v9
	v_exp_f32_e32 v12, v12
	v_mul_f32_e32 v8, v8, v10
	v_add_f32_e32 v10, 1.0, v11
	v_fma_f32 v11, -v9, v9, 1.0
	ds_write2st64_b32 v4, v7, v9 offset0:24 offset1:25
	v_add_f32_e32 v9, 1.0, v12
	v_rcp_f32_e32 v9, v9
	v_max_f32_e32 v11, 0, v11
	v_rcp_f32_e32 v10, v10
	v_sqrt_f32_e32 v11, v11
	v_mul_f32_e32 v9, 0xc1000000, v9
	v_mul_f32_e32 v9, v9, v20
	v_mul_f32_e32 v9, 0x3fb8aa3b, v9
	v_mul_f32_e32 v7, v10, v11
	v_add_f32_e32 v10, v65, v0
	v_mul_f32_e32 v10, 0xbfb8aa3b, v10
	v_exp_f32_e32 v9, v9
	v_cvt_f32_f16_e32 v75, v128
	v_cvt_f32_f16_e32 v73, v129
	v_exp_f32_e32 v10, v10
	v_fma_f32 v11, -v9, v9, 1.0
	v_mul_f32_e32 v5, v5, v75
	v_mul_f32_e32 v7, v7, v73
	v_add_f32_e32 v10, 1.0, v10
	v_max_f32_e32 v11, 0, v11
	v_rcp_f32_e32 v10, v10
	v_sqrt_f32_e32 v11, v11
	ds_write2st64_b32 v4, v5, v7 offset0:152 offset1:153
	ds_write2st64_b32 v4, v6, v9 offset0:56 offset1:57
	v_add_f32_e32 v7, v18, v0
	v_cvt_f32_f16_e32 v74, v136
	v_cvt_f32_f16_e32 v72, v137
	v_mul_f32_e32 v7, 0xbfb8aa3b, v7
	v_exp_f32_e32 v7, v7
	v_mul_f32_e32 v5, v10, v11
	v_mul_f32_e32 v8, v8, v74
	v_mul_f32_e32 v5, v5, v72
	v_add_f32_e32 v12, v34, v1
	ds_write2st64_b32 v4, v8, v5 offset0:184 offset1:185
	v_add_f32_e32 v5, 1.0, v7
	v_add_f32_e32 v7, v50, v1
	v_mul_f32_e32 v12, 0xbfb8aa3b, v12
	v_mul_f32_e32 v7, 0xbfb8aa3b, v7
	v_exp_f32_e32 v12, v12
	v_exp_f32_e32 v7, v7
	v_add_f32_e32 v9, v66, v0
	v_mul_f32_e32 v9, 0xbfb8aa3b, v9
	v_add_f32_e32 v6, 1.0, v12
	v_add_f32_e32 v7, 1.0, v7
	v_rcp_f32_e32 v6, v6
	v_rcp_f32_e32 v7, v7
	v_exp_f32_e32 v9, v9
	v_add_f32_e32 v11, v35, v1
	v_mul_f32_e32 v6, 0xc1000000, v6
	v_mul_f32_e32 v7, 0xc1000000, v7
	v_mul_f32_e32 v6, v6, v20
	v_mul_f32_e32 v7, v7, v20
	v_mul_f32_e32 v6, 0x3fb8aa3b, v6
	v_mul_f32_e32 v7, 0x3fb8aa3b, v7
	v_exp_f32_e32 v6, v6
	v_exp_f32_e32 v7, v7
	v_add_f32_e32 v1, v51, v1
	v_add_f32_e32 v9, 1.0, v9
	v_fma_f32 v8, -v6, v6, 1.0
	v_fma_f32 v10, -v7, v7, 1.0
	v_max_f32_e32 v8, 0, v8
	v_max_f32_e32 v10, 0, v10
	v_mul_f32_e32 v11, 0xbfb8aa3b, v11
	v_mul_f32_e32 v1, 0xbfb8aa3b, v1
	v_rcp_f32_e32 v5, v5
	v_sqrt_f32_e32 v8, v8
	v_rcp_f32_e32 v9, v9
	v_sqrt_f32_e32 v10, v10
	v_exp_f32_e32 v11, v11
	v_exp_f32_e32 v1, v1
	v_mul_f32_e32 v5, v5, v8
	v_mul_f32_e32 v8, v9, v10
	v_add_f32_e32 v9, 1.0, v11
	v_add_f32_e32 v1, 1.0, v1
	v_rcp_f32_e32 v9, v9
	v_rcp_f32_e32 v1, v1
	v_add_f32_e32 v10, v19, v0
	v_add_f32_e32 v0, v67, v0
	v_mul_f32_e32 v9, 0xc1000000, v9
	v_mul_f32_e32 v1, 0xc1000000, v1
	v_mul_f32_e32 v9, v9, v20
	v_mul_f32_e32 v1, v1, v20
	v_mul_f32_e32 v9, 0x3fb8aa3b, v9
	v_mul_f32_e32 v1, 0x3fb8aa3b, v1
	v_mul_f32_e32 v10, 0xbfb8aa3b, v10
	v_exp_f32_e32 v9, v9
	v_mul_f32_e32 v0, 0xbfb8aa3b, v0
	v_exp_f32_e32 v1, v1
	v_exp_f32_e32 v10, v10
	v_exp_f32_e32 v0, v0
	ds_write2st64_b32 v4, v6, v9 offset0:26 offset1:27
	v_fma_f32 v6, -v9, v9, 1.0
	v_fma_f32 v9, -v1, v1, 1.0
	v_add_f32_e32 v10, 1.0, v10
	v_max_f32_e32 v6, 0, v6
	v_add_f32_e32 v0, 1.0, v0
	v_max_f32_e32 v9, 0, v9
	v_rcp_f32_e32 v10, v10
	v_sqrt_f32_e32 v6, v6
	v_rcp_f32_e32 v0, v0
	v_sqrt_f32_e32 v9, v9
	v_cvt_f32_f16_e32 v71, v130
	v_cvt_f32_f16_e32 v70, v138
	v_cvt_f32_f16_e32 v69, v131
	v_mul_f32_e32 v6, v10, v6
	v_mul_f32_e32 v0, v0, v9
	s_movk_i32 s26, 0x80
	v_mul_f32_e32 v5, v5, v71
	v_mul_f32_e32 v8, v8, v70
	v_mul_f32_e32 v6, v6, v69
	v_mul_f32_e32 v0, v0, v2
	v_cmp_lt_u32_sdwa s[28:29], v68, s26 src0_sel:BYTE_0 src1_sel:DWORD
	ds_write2st64_b32 v4, v5, v6 offset0:154 offset1:155
	ds_write2st64_b32 v4, v7, v1 offset0:58 offset1:59
	ds_write2st64_b32 v4, v8, v0 offset0:186 offset1:187
	s_waitcnt lgkmcnt(0)
	s_barrier
	s_and_saveexec_b64 s[26:27], s[28:29]
	s_cbranch_execz .LBB0_935
	v_and_b32_e32 v2, 63, v68
	v_lshrrev_b32_sdwa v20, v214, v68 dst_sel:DWORD dst_unused:UNUSED_PAD src0_sel:DWORD src1_sel:BYTE_0
	v_lshlrev_b32_e32 v0, 14, v20
	v_lshlrev_b32_e32 v1, 2, v2
	v_add3_u32 v21, s35, v0, v1
	v_cmp_lt_u32_sdwa vcc, v68, v220 src0_sel:BYTE_0 src1_sel:DWORD
	v_cmp_gt_u32_sdwa s[28:29], v68, v221 src0_sel:BYTE_0 src1_sel:DWORD
	v_mov_b32_e32 v1, 0
	v_mov_b32_e32 v0, 1.0
	s_mov_b32 s35, 56
	s_mov_b32 s42, 0
	s_branch .LBB0_1111
